# norm1/norm2 row loops hand-rewritten: all loads of the next row group (x, partials, modulation, pos-emb) prefetched together, one counted wait per group (was: a vmcnt(0) drain behind every pos-emb loa
# speedup vs baseline: 1.0054x; 1.0054x over previous
.LBB0_96:
	s_or_b64 exec, exec, s[4:5]
	s_load_dwordx16 s[4:19], s[0:1], 0x40
	s_waitcnt lgkmcnt(0)
	v_mov_b32_e32 v0, v195
	s_barrier
	v_writelane_b32 v254, s4, 5
	s_nop 0
	v_ashrrev_i32_e32 v64, 4, v0
	v_writelane_b32 v254, s5, 6
	v_writelane_b32 v254, s6, 7
	v_writelane_b32 v254, s7, 8
	v_writelane_b32 v254, s8, 9
	v_writelane_b32 v254, s9, 10
	v_writelane_b32 v254, s10, 11
	v_writelane_b32 v254, s11, 12
	v_writelane_b32 v254, s12, 13
	v_writelane_b32 v254, s13, 14
	v_writelane_b32 v254, s14, 15
	v_writelane_b32 v254, s15, 16
	v_writelane_b32 v254, s16, 17
	v_writelane_b32 v254, s17, 18
	v_writelane_b32 v254, s18, 19
	v_writelane_b32 v254, s19, 20
	s_load_dwordx16 s[4:19], s[0:1], 0x80
	v_and_b32_e32 v65, 63, v0
	v_and_b32_e32 v0, -4, v64
	v_lshl_add_u32 v184, s2, 5, v0
	s_movk_i32 s0, 0x5000
	s_waitcnt lgkmcnt(0)
	v_writelane_b32 v254, s4, 21
	v_cmp_gt_i32_e32 vcc, s0, v184
	v_lshlrev_b32_e32 v160, 4, v65
	v_writelane_b32 v254, s5, 22
	v_writelane_b32 v254, s6, 23
	v_writelane_b32 v254, s7, 24
	v_writelane_b32 v254, s8, 25
	v_writelane_b32 v254, s9, 26
	v_writelane_b32 v254, s10, 27
	v_writelane_b32 v254, s11, 28
	v_writelane_b32 v254, s12, 29
	v_writelane_b32 v254, s13, 30
	v_writelane_b32 v254, s14, 31
	v_writelane_b32 v254, s15, 32
	v_writelane_b32 v254, s16, 33
	v_writelane_b32 v254, s17, 34
	v_writelane_b32 v254, s18, 35
	v_writelane_b32 v254, s19, 36
	s_add_u32 s78, s30, 0x840000
	s_addc_u32 s79, s31, 0
	s_add_u32 s34, s30, 0x8d2000
	s_addc_u32 s35, s31, 0
	s_lshl_b32 s33, s86, 5
	v_and_b32_e32 v0, 63, v195
	v_lshlrev_b32_e32 v2, 4, v0
	v_lshlrev_b32_e32 v3, 3, v0
	v_xor_b32_e32 v5, 1, v0
	v_lshlrev_b32_e32 v5, 2, v5
	v_xor_b32_e32 v6, 2, v0
	v_lshlrev_b32_e32 v6, 2, v6
	v_xor_b32_e32 v7, 4, v0
	v_lshlrev_b32_e32 v7, 2, v7
	v_xor_b32_e32 v8, 8, v0
	v_lshlrev_b32_e32 v8, 2, v8
	v_xor_b32_e32 v9, 16, v0
	v_lshlrev_b32_e32 v9, 2, v9
	v_xor_b32_e32 v10, 32, v0
	v_lshlrev_b32_e32 v10, 2, v10
	v_mov_b32_e32 v4, 0x358637bd
	v_readfirstlane_b32 s0, v195
	s_nop 1
	s_lshr_b32 s0, s0, 6
	s_lshl_b32 s1, s2, 3
	s_add_u32 s0, s0, s1
	s_mul_i32 s22, s0, 2
	s_mul_i32 s23, s86, 16
	s_cmp_lt_u32 s22, 0x5000
	s_cbranch_scc0 .Lnm1_exit
	global_load_dwordx4 v[20:23], v2, s[66:67]
	global_load_dwordx4 v[24:27], v2, s[66:67] offset:1024
	global_load_dwordx4 v[28:31], v2, s[66:67] offset:2048
	global_load_dwordx4 v[32:35], v2, s[66:67] offset:3072
	s_mov_b32 s0, s22
	s_cmp_lt_u32 s0, 0x1000
	s_cselect_b32 s10, s52, s54
	s_cselect_b32 s11, s53, s55
	s_cselect_b32 s1, 0, 0x1000
	s_sub_u32 s1, s0, s1
	s_lshl_b32 s1, s1, 12
	s_add_u32 s10, s10, s1
	s_addc_u32 s11, s11, 0
	global_load_dwordx4 v[124:127], v2, s[10:11] nt
	global_load_dwordx4 v[128:131], v2, s[10:11] offset:1024 nt
	global_load_dwordx4 v[132:135], v2, s[10:11] offset:2048 nt
	global_load_dwordx4 v[136:139], v2, s[10:11] offset:3072 nt
	s_add_u32 s0, s22, 1
	s_cmp_lt_u32 s0, 0x1000
	s_cselect_b32 s10, s52, s54
	s_cselect_b32 s11, s53, s55
	s_cselect_b32 s1, 0, 0x1000
	s_sub_u32 s1, s0, s1
	s_lshl_b32 s1, s1, 12
	s_add_u32 s10, s10, s1
	s_addc_u32 s11, s11, 0
	global_load_dwordx4 v[140:143], v2, s[10:11] nt
	global_load_dwordx4 v[144:147], v2, s[10:11] offset:1024 nt
	global_load_dwordx4 v[148:151], v2, s[10:11] offset:2048 nt
	global_load_dwordx4 v[152:155], v2, s[10:11] offset:3072 nt
	s_sub_u32 s1, s22, 0x1000
	s_lshr_b32 s1, s1, 12
	s_add_u32 s1, s1, 1
	s_cmp_lt_u32 s22, 0x1000
	s_cselect_b32 s1, 0, s1
	s_mul_i32 s1, s1, 0x6000
	s_add_u32 s14, s30, 0x840000
	s_addc_u32 s15, s31, 0
	s_add_u32 s14, s14, s1
	s_addc_u32 s15, s15, 0
	s_add_u32 s16, s14, 0x1000
	s_addc_u32 s17, s15, 0
	global_load_dwordx4 v[84:87], v2, s[14:15]
	global_load_dwordx4 v[88:91], v2, s[14:15] offset:1024
	global_load_dwordx4 v[92:95], v2, s[14:15] offset:2048
	global_load_dwordx4 v[96:99], v2, s[14:15] offset:3072
	global_load_dwordx4 v[68:71], v2, s[16:17]
	global_load_dwordx4 v[72:75], v2, s[16:17] offset:1024
	global_load_dwordx4 v[76:79], v2, s[16:17] offset:2048
	global_load_dwordx4 v[80:83], v2, s[16:17] offset:3072
	s_add_u32 s18, s30, 0x85e000
	s_addc_u32 s19, s31, 0
	s_bfe_u32 s1, s22, 0x60006
	s_lshl_b32 s1, s1, 11
	s_add_u32 s20, s18, s1
	s_addc_u32 s21, s19, 0
	global_load_dwordx4 v[100:103], v2, s[20:21]
	global_load_dwordx4 v[104:107], v2, s[20:21] offset:1024
	s_and_b32 s1, s22, 63
	s_lshl_b32 s1, s1, 11
	s_add_u32 s20, s18, s1
	s_addc_u32 s21, s19, 0
	global_load_dwordx4 v[108:111], v2, s[20:21]
	global_load_dwordx4 v[112:115], v2, s[20:21] offset:1024
	global_load_dwordx4 v[116:119], v2, s[20:21] offset:2048
	global_load_dwordx4 v[120:123], v2, s[20:21] offset:3072
	s_waitcnt vmcnt(0)
	s_branch .Lnm1_go0

.Lnm1_go0:
	v_pk_add_f32 v[36:37], v[68:69], 1.0 op_sel_hi:[1,0]
	v_pk_add_f32 v[38:39], v[70:71], 1.0 op_sel_hi:[1,0]
	v_pk_add_f32 v[40:41], v[72:73], 1.0 op_sel_hi:[1,0]
	v_pk_add_f32 v[42:43], v[74:75], 1.0 op_sel_hi:[1,0]
	v_pk_add_f32 v[44:45], v[76:77], 1.0 op_sel_hi:[1,0]
	v_pk_add_f32 v[46:47], v[78:79], 1.0 op_sel_hi:[1,0]
	v_pk_add_f32 v[48:49], v[80:81], 1.0 op_sel_hi:[1,0]
	v_pk_add_f32 v[50:51], v[82:83], 1.0 op_sel_hi:[1,0]
	v_pk_mul_f32 v[36:37], v[20:21], v[36:37]
	v_pk_mul_f32 v[38:39], v[22:23], v[38:39]
	v_pk_mul_f32 v[40:41], v[24:25], v[40:41]
	v_pk_mul_f32 v[42:43], v[26:27], v[42:43]
	v_pk_mul_f32 v[44:45], v[28:29], v[44:45]
	v_pk_mul_f32 v[46:47], v[30:31], v[46:47]
	v_pk_mul_f32 v[48:49], v[32:33], v[48:49]
	v_pk_mul_f32 v[50:51], v[34:35], v[50:51]
	v_mov_b32_e32 v52, v84
	v_mov_b32_e32 v53, v85
	v_mov_b32_e32 v54, v86
	v_mov_b32_e32 v55, v87
	v_mov_b32_e32 v56, v88
	v_mov_b32_e32 v57, v89
	v_mov_b32_e32 v58, v90
	v_mov_b32_e32 v59, v91
	v_mov_b32_e32 v60, v92
	v_mov_b32_e32 v61, v93
	v_mov_b32_e32 v62, v94
	v_mov_b32_e32 v63, v95
	v_mov_b32_e32 v64, v96
	v_mov_b32_e32 v65, v97
	v_mov_b32_e32 v66, v98
	v_mov_b32_e32 v67, v99
	s_cmp_lt_u32 s22, 0x1000
	s_cbranch_scc1 .Lnm1_nope0
	v_pk_add_f32 v[124:125], v[124:125], v[100:101]
	v_pk_add_f32 v[126:127], v[126:127], v[102:103]
	v_pk_add_f32 v[128:129], v[128:129], v[104:105]
	v_pk_add_f32 v[130:131], v[130:131], v[106:107]
	v_pk_add_f32 v[132:133], v[132:133], v[108:109]
	v_pk_add_f32 v[134:135], v[134:135], v[110:111]
	v_pk_add_f32 v[136:137], v[136:137], v[112:113]
	v_pk_add_f32 v[138:139], v[138:139], v[114:115]
	v_pk_add_f32 v[140:141], v[140:141], v[100:101]
	v_pk_add_f32 v[142:143], v[142:143], v[102:103]
	v_pk_add_f32 v[144:145], v[144:145], v[104:105]
	v_pk_add_f32 v[146:147], v[146:147], v[106:107]
	v_pk_add_f32 v[148:149], v[148:149], v[116:117]
	v_pk_add_f32 v[150:151], v[150:151], v[118:119]
	v_pk_add_f32 v[152:153], v[152:153], v[120:121]
	v_pk_add_f32 v[154:155], v[154:155], v[122:123]
.Lnm1_nope0:
	s_add_u32 s3, s22, s23
	s_cmp_lt_u32 s3, 0x5000
	s_cbranch_scc0 .Lnm1_nopf0
	s_mov_b32 s0, s3
	s_cmp_lt_u32 s0, 0x1000
	s_cselect_b32 s10, s52, s54
	s_cselect_b32 s11, s53, s55
	s_cselect_b32 s1, 0, 0x1000
	s_sub_u32 s1, s0, s1
	s_lshl_b32 s1, s1, 12
	s_add_u32 s10, s10, s1
	s_addc_u32 s11, s11, 0
	global_load_dwordx4 v[156:159], v2, s[10:11] nt
	global_load_dwordx4 v[160:163], v2, s[10:11] offset:1024 nt
	global_load_dwordx4 v[164:167], v2, s[10:11] offset:2048 nt
	global_load_dwordx4 v[168:171], v2, s[10:11] offset:3072 nt
	s_add_u32 s0, s3, 1
	s_cmp_lt_u32 s0, 0x1000
	s_cselect_b32 s10, s52, s54
	s_cselect_b32 s11, s53, s55
	s_cselect_b32 s1, 0, 0x1000
	s_sub_u32 s1, s0, s1
	s_lshl_b32 s1, s1, 12
	s_add_u32 s10, s10, s1
	s_addc_u32 s11, s11, 0
	global_load_dwordx4 v[172:175], v2, s[10:11] nt
	global_load_dwordx4 v[176:179], v2, s[10:11] offset:1024 nt
	global_load_dwordx4 v[180:183], v2, s[10:11] offset:2048 nt
	global_load_dwordx4 v[184:187], v2, s[10:11] offset:3072 nt
	s_sub_u32 s1, s3, 0x1000
	s_lshr_b32 s1, s1, 12
	s_add_u32 s1, s1, 1
	s_cmp_lt_u32 s3, 0x1000
	s_cselect_b32 s1, 0, s1
	s_mul_i32 s1, s1, 0x6000
	s_add_u32 s14, s30, 0x840000
	s_addc_u32 s15, s31, 0
	s_add_u32 s14, s14, s1
	s_addc_u32 s15, s15, 0
	s_add_u32 s16, s14, 0x1000
	s_addc_u32 s17, s15, 0
	global_load_dwordx4 v[84:87], v2, s[14:15]
	global_load_dwordx4 v[88:91], v2, s[14:15] offset:1024
	global_load_dwordx4 v[92:95], v2, s[14:15] offset:2048
	global_load_dwordx4 v[96:99], v2, s[14:15] offset:3072
	global_load_dwordx4 v[68:71], v2, s[16:17]
	global_load_dwordx4 v[72:75], v2, s[16:17] offset:1024
	global_load_dwordx4 v[76:79], v2, s[16:17] offset:2048
	global_load_dwordx4 v[80:83], v2, s[16:17] offset:3072
	s_add_u32 s18, s30, 0x85e000
	s_addc_u32 s19, s31, 0
	s_bfe_u32 s1, s3, 0x60006
	s_lshl_b32 s1, s1, 11
	s_add_u32 s20, s18, s1
	s_addc_u32 s21, s19, 0
	global_load_dwordx4 v[100:103], v2, s[20:21]
	global_load_dwordx4 v[104:107], v2, s[20:21] offset:1024
	s_and_b32 s1, s3, 63
	s_lshl_b32 s1, s1, 11
	s_add_u32 s20, s18, s1
	s_addc_u32 s21, s19, 0
	global_load_dwordx4 v[108:111], v2, s[20:21]
	global_load_dwordx4 v[112:115], v2, s[20:21] offset:1024
	global_load_dwordx4 v[116:119], v2, s[20:21] offset:2048
	global_load_dwordx4 v[120:123], v2, s[20:21] offset:3072
.Lnm1_nopf0:
	v_pk_mul_f32 v[12:13], v[124:125], v[124:125]
	v_pk_fma_f32 v[12:13], v[126:127], v[126:127], v[12:13]
	v_pk_fma_f32 v[12:13], v[128:129], v[128:129], v[12:13]
	v_pk_fma_f32 v[12:13], v[130:131], v[130:131], v[12:13]
	v_pk_fma_f32 v[12:13], v[132:133], v[132:133], v[12:13]
	v_pk_fma_f32 v[12:13], v[134:135], v[134:135], v[12:13]
	v_pk_fma_f32 v[12:13], v[136:137], v[136:137], v[12:13]
	v_pk_fma_f32 v[12:13], v[138:139], v[138:139], v[12:13]
	v_pk_mul_f32 v[14:15], v[140:141], v[140:141]
	v_pk_fma_f32 v[14:15], v[142:143], v[142:143], v[14:15]
	v_pk_fma_f32 v[14:15], v[144:145], v[144:145], v[14:15]
	v_pk_fma_f32 v[14:15], v[146:147], v[146:147], v[14:15]
	v_pk_fma_f32 v[14:15], v[148:149], v[148:149], v[14:15]
	v_pk_fma_f32 v[14:15], v[150:151], v[150:151], v[14:15]
	v_pk_fma_f32 v[14:15], v[152:153], v[152:153], v[14:15]
	v_pk_fma_f32 v[14:15], v[154:155], v[154:155], v[14:15]
	v_add_f32_e32 v12, v12, v13
	v_add_f32_e32 v14, v14, v15
	ds_bpermute_b32 v208, v5, v12
	ds_bpermute_b32 v209, v5, v14
	s_waitcnt lgkmcnt(1)
	v_add_f32_e32 v12, v12, v208
	s_waitcnt lgkmcnt(0)
	v_add_f32_e32 v14, v14, v209
	ds_bpermute_b32 v208, v6, v12
	ds_bpermute_b32 v209, v6, v14
	s_waitcnt lgkmcnt(1)
	v_add_f32_e32 v12, v12, v208
	s_waitcnt lgkmcnt(0)
	v_add_f32_e32 v14, v14, v209
	ds_bpermute_b32 v208, v7, v12
	ds_bpermute_b32 v209, v7, v14
	s_waitcnt lgkmcnt(1)
	v_add_f32_e32 v12, v12, v208
	s_waitcnt lgkmcnt(0)
	v_add_f32_e32 v14, v14, v209
	ds_bpermute_b32 v208, v8, v12
	ds_bpermute_b32 v209, v8, v14
	s_waitcnt lgkmcnt(1)
	v_add_f32_e32 v12, v12, v208
	s_waitcnt lgkmcnt(0)
	v_add_f32_e32 v14, v14, v209
	ds_bpermute_b32 v208, v9, v12
	ds_bpermute_b32 v209, v9, v14
	s_waitcnt lgkmcnt(1)
	v_add_f32_e32 v12, v12, v208
	s_waitcnt lgkmcnt(0)
	v_add_f32_e32 v14, v14, v209
	ds_bpermute_b32 v208, v10, v12
	ds_bpermute_b32 v209, v10, v14
	s_waitcnt lgkmcnt(1)
	v_add_f32_e32 v12, v12, v208
	s_waitcnt lgkmcnt(0)
	v_add_f32_e32 v14, v14, v209
	v_fmamk_f32 v16, v12, 0x3a800000, v4
	v_fmamk_f32 v18, v14, 0x3a800000, v4
	v_rsq_f32_e32 v16, v16
	v_rsq_f32_e32 v18, v18
	s_nop 0
	s_mov_b32 s0, s22
	s_lshl_b32 s1, s0, 11
	s_add_u32 s12, s30, 0x8d2000
	s_addc_u32 s13, s31, 0
	s_add_u32 s12, s12, s1
	s_addc_u32 s13, s13, 0
	v_pk_mul_f32 v[196:197], v[124:125], v[16:17] op_sel_hi:[1,0]
	v_pk_mul_f32 v[198:199], v[126:127], v[16:17] op_sel_hi:[1,0]
	v_pk_fma_f32 v[196:197], v[36:37], v[196:197], v[52:53]
	v_pk_fma_f32 v[198:199], v[38:39], v[198:199], v[54:55]
	v_cvt_pk_bf16_f32 v204, v196, v197
	v_cvt_pk_bf16_f32 v205, v198, v199
	global_store_dwordx2 v3, v[204:205], s[12:13]
	v_pk_mul_f32 v[200:201], v[128:129], v[16:17] op_sel_hi:[1,0]
	v_pk_mul_f32 v[202:203], v[130:131], v[16:17] op_sel_hi:[1,0]
	v_pk_fma_f32 v[200:201], v[40:41], v[200:201], v[56:57]
	v_pk_fma_f32 v[202:203], v[42:43], v[202:203], v[58:59]
	v_cvt_pk_bf16_f32 v206, v200, v201
	v_cvt_pk_bf16_f32 v207, v202, v203
	global_store_dwordx2 v3, v[206:207], s[12:13] offset:512
	v_pk_mul_f32 v[196:197], v[132:133], v[16:17] op_sel_hi:[1,0]
	v_pk_mul_f32 v[198:199], v[134:135], v[16:17] op_sel_hi:[1,0]
	v_pk_fma_f32 v[196:197], v[44:45], v[196:197], v[60:61]
	v_pk_fma_f32 v[198:199], v[46:47], v[198:199], v[62:63]
	v_cvt_pk_bf16_f32 v204, v196, v197
	v_cvt_pk_bf16_f32 v205, v198, v199
	global_store_dwordx2 v3, v[204:205], s[12:13] offset:1024
	v_pk_mul_f32 v[200:201], v[136:137], v[16:17] op_sel_hi:[1,0]
	v_pk_mul_f32 v[202:203], v[138:139], v[16:17] op_sel_hi:[1,0]
	v_pk_fma_f32 v[200:201], v[48:49], v[200:201], v[64:65]
	v_pk_fma_f32 v[202:203], v[50:51], v[202:203], v[66:67]
	v_cvt_pk_bf16_f32 v206, v200, v201
	v_cvt_pk_bf16_f32 v207, v202, v203
	global_store_dwordx2 v3, v[206:207], s[12:13] offset:1536
	s_add_u32 s0, s22, 1
	s_lshl_b32 s1, s0, 11
	s_add_u32 s12, s30, 0x8d2000
	s_addc_u32 s13, s31, 0
	s_add_u32 s12, s12, s1
	s_addc_u32 s13, s13, 0
	v_pk_mul_f32 v[196:197], v[140:141], v[18:19] op_sel_hi:[1,0]
	v_pk_mul_f32 v[198:199], v[142:143], v[18:19] op_sel_hi:[1,0]
	v_pk_fma_f32 v[196:197], v[36:37], v[196:197], v[52:53]
	v_pk_fma_f32 v[198:199], v[38:39], v[198:199], v[54:55]
	v_cvt_pk_bf16_f32 v204, v196, v197
	v_cvt_pk_bf16_f32 v205, v198, v199
	global_store_dwordx2 v3, v[204:205], s[12:13]
	v_pk_mul_f32 v[200:201], v[144:145], v[18:19] op_sel_hi:[1,0]
	v_pk_mul_f32 v[202:203], v[146:147], v[18:19] op_sel_hi:[1,0]
	v_pk_fma_f32 v[200:201], v[40:41], v[200:201], v[56:57]
	v_pk_fma_f32 v[202:203], v[42:43], v[202:203], v[58:59]
	v_cvt_pk_bf16_f32 v206, v200, v201
	v_cvt_pk_bf16_f32 v207, v202, v203
	global_store_dwordx2 v3, v[206:207], s[12:13] offset:512
	v_pk_mul_f32 v[196:197], v[148:149], v[18:19] op_sel_hi:[1,0]
	v_pk_mul_f32 v[198:199], v[150:151], v[18:19] op_sel_hi:[1,0]
	v_pk_fma_f32 v[196:197], v[44:45], v[196:197], v[60:61]
	v_pk_fma_f32 v[198:199], v[46:47], v[198:199], v[62:63]
	v_cvt_pk_bf16_f32 v204, v196, v197
	v_cvt_pk_bf16_f32 v205, v198, v199
	global_store_dwordx2 v3, v[204:205], s[12:13] offset:1024
	v_pk_mul_f32 v[200:201], v[152:153], v[18:19] op_sel_hi:[1,0]
	v_pk_mul_f32 v[202:203], v[154:155], v[18:19] op_sel_hi:[1,0]
	v_pk_fma_f32 v[200:201], v[48:49], v[200:201], v[64:65]
	v_pk_fma_f32 v[202:203], v[50:51], v[202:203], v[66:67]
	v_cvt_pk_bf16_f32 v206, v200, v201
	v_cvt_pk_bf16_f32 v207, v202, v203
	global_store_dwordx2 v3, v[206:207], s[12:13] offset:1536
	s_mov_b32 s22, s3
	s_cmp_lt_u32 s22, 0x5000
	s_cbranch_scc0 .Lnm1_exit

.Lnm1_go1:
	v_pk_add_f32 v[36:37], v[68:69], 1.0 op_sel_hi:[1,0]
	v_pk_add_f32 v[38:39], v[70:71], 1.0 op_sel_hi:[1,0]
	v_pk_add_f32 v[40:41], v[72:73], 1.0 op_sel_hi:[1,0]
	v_pk_add_f32 v[42:43], v[74:75], 1.0 op_sel_hi:[1,0]
	v_pk_add_f32 v[44:45], v[76:77], 1.0 op_sel_hi:[1,0]
	v_pk_add_f32 v[46:47], v[78:79], 1.0 op_sel_hi:[1,0]
	v_pk_add_f32 v[48:49], v[80:81], 1.0 op_sel_hi:[1,0]
	v_pk_add_f32 v[50:51], v[82:83], 1.0 op_sel_hi:[1,0]
	v_pk_mul_f32 v[36:37], v[20:21], v[36:37]
	v_pk_mul_f32 v[38:39], v[22:23], v[38:39]
	v_pk_mul_f32 v[40:41], v[24:25], v[40:41]
	v_pk_mul_f32 v[42:43], v[26:27], v[42:43]
	v_pk_mul_f32 v[44:45], v[28:29], v[44:45]
	v_pk_mul_f32 v[46:47], v[30:31], v[46:47]
	v_pk_mul_f32 v[48:49], v[32:33], v[48:49]
	v_pk_mul_f32 v[50:51], v[34:35], v[50:51]
	v_mov_b32_e32 v52, v84
	v_mov_b32_e32 v53, v85
	v_mov_b32_e32 v54, v86
	v_mov_b32_e32 v55, v87
	v_mov_b32_e32 v56, v88
	v_mov_b32_e32 v57, v89
	v_mov_b32_e32 v58, v90
	v_mov_b32_e32 v59, v91
	v_mov_b32_e32 v60, v92
	v_mov_b32_e32 v61, v93
	v_mov_b32_e32 v62, v94
	v_mov_b32_e32 v63, v95
	v_mov_b32_e32 v64, v96
	v_mov_b32_e32 v65, v97
	v_mov_b32_e32 v66, v98
	v_mov_b32_e32 v67, v99
	s_cmp_lt_u32 s22, 0x1000
	s_cbranch_scc1 .Lnm1_nope1
	v_pk_add_f32 v[156:157], v[156:157], v[100:101]
	v_pk_add_f32 v[158:159], v[158:159], v[102:103]
	v_pk_add_f32 v[160:161], v[160:161], v[104:105]
	v_pk_add_f32 v[162:163], v[162:163], v[106:107]
	v_pk_add_f32 v[164:165], v[164:165], v[108:109]
	v_pk_add_f32 v[166:167], v[166:167], v[110:111]
	v_pk_add_f32 v[168:169], v[168:169], v[112:113]
	v_pk_add_f32 v[170:171], v[170:171], v[114:115]
	v_pk_add_f32 v[172:173], v[172:173], v[100:101]
	v_pk_add_f32 v[174:175], v[174:175], v[102:103]
	v_pk_add_f32 v[176:177], v[176:177], v[104:105]
	v_pk_add_f32 v[178:179], v[178:179], v[106:107]
	v_pk_add_f32 v[180:181], v[180:181], v[116:117]
	v_pk_add_f32 v[182:183], v[182:183], v[118:119]
	v_pk_add_f32 v[184:185], v[184:185], v[120:121]
	v_pk_add_f32 v[186:187], v[186:187], v[122:123]
.Lnm1_nope1:
	s_add_u32 s3, s22, s23
	s_cmp_lt_u32 s3, 0x5000
	s_cbranch_scc0 .Lnm1_nopf1
	s_mov_b32 s0, s3
	s_cmp_lt_u32 s0, 0x1000
	s_cselect_b32 s10, s52, s54
	s_cselect_b32 s11, s53, s55
	s_cselect_b32 s1, 0, 0x1000
	s_sub_u32 s1, s0, s1
	s_lshl_b32 s1, s1, 12
	s_add_u32 s10, s10, s1
	s_addc_u32 s11, s11, 0
	global_load_dwordx4 v[124:127], v2, s[10:11] nt
	global_load_dwordx4 v[128:131], v2, s[10:11] offset:1024 nt
	global_load_dwordx4 v[132:135], v2, s[10:11] offset:2048 nt
	global_load_dwordx4 v[136:139], v2, s[10:11] offset:3072 nt
	s_add_u32 s0, s3, 1
	s_cmp_lt_u32 s0, 0x1000
	s_cselect_b32 s10, s52, s54
	s_cselect_b32 s11, s53, s55
	s_cselect_b32 s1, 0, 0x1000
	s_sub_u32 s1, s0, s1
	s_lshl_b32 s1, s1, 12
	s_add_u32 s10, s10, s1
	s_addc_u32 s11, s11, 0
	global_load_dwordx4 v[140:143], v2, s[10:11] nt
	global_load_dwordx4 v[144:147], v2, s[10:11] offset:1024 nt
	global_load_dwordx4 v[148:151], v2, s[10:11] offset:2048 nt
	global_load_dwordx4 v[152:155], v2, s[10:11] offset:3072 nt
	s_sub_u32 s1, s3, 0x1000
	s_lshr_b32 s1, s1, 12
	s_add_u32 s1, s1, 1
	s_cmp_lt_u32 s3, 0x1000
	s_cselect_b32 s1, 0, s1
	s_mul_i32 s1, s1, 0x6000
	s_add_u32 s14, s30, 0x840000
	s_addc_u32 s15, s31, 0
	s_add_u32 s14, s14, s1
	s_addc_u32 s15, s15, 0
	s_add_u32 s16, s14, 0x1000
	s_addc_u32 s17, s15, 0
	global_load_dwordx4 v[84:87], v2, s[14:15]
	global_load_dwordx4 v[88:91], v2, s[14:15] offset:1024
	global_load_dwordx4 v[92:95], v2, s[14:15] offset:2048
	global_load_dwordx4 v[96:99], v2, s[14:15] offset:3072
	global_load_dwordx4 v[68:71], v2, s[16:17]
	global_load_dwordx4 v[72:75], v2, s[16:17] offset:1024
	global_load_dwordx4 v[76:79], v2, s[16:17] offset:2048
	global_load_dwordx4 v[80:83], v2, s[16:17] offset:3072
	s_add_u32 s18, s30, 0x85e000
	s_addc_u32 s19, s31, 0
	s_bfe_u32 s1, s3, 0x60006
	s_lshl_b32 s1, s1, 11
	s_add_u32 s20, s18, s1
	s_addc_u32 s21, s19, 0
	global_load_dwordx4 v[100:103], v2, s[20:21]
	global_load_dwordx4 v[104:107], v2, s[20:21] offset:1024
	s_and_b32 s1, s3, 63
	s_lshl_b32 s1, s1, 11
	s_add_u32 s20, s18, s1
	s_addc_u32 s21, s19, 0
	global_load_dwordx4 v[108:111], v2, s[20:21]
	global_load_dwordx4 v[112:115], v2, s[20:21] offset:1024
	global_load_dwordx4 v[116:119], v2, s[20:21] offset:2048
	global_load_dwordx4 v[120:123], v2, s[20:21] offset:3072
.Lnm1_nopf1:
	v_pk_mul_f32 v[12:13], v[156:157], v[156:157]
	v_pk_fma_f32 v[12:13], v[158:159], v[158:159], v[12:13]
	v_pk_fma_f32 v[12:13], v[160:161], v[160:161], v[12:13]
	v_pk_fma_f32 v[12:13], v[162:163], v[162:163], v[12:13]
	v_pk_fma_f32 v[12:13], v[164:165], v[164:165], v[12:13]
	v_pk_fma_f32 v[12:13], v[166:167], v[166:167], v[12:13]
	v_pk_fma_f32 v[12:13], v[168:169], v[168:169], v[12:13]
	v_pk_fma_f32 v[12:13], v[170:171], v[170:171], v[12:13]
	v_pk_mul_f32 v[14:15], v[172:173], v[172:173]
	v_pk_fma_f32 v[14:15], v[174:175], v[174:175], v[14:15]
	v_pk_fma_f32 v[14:15], v[176:177], v[176:177], v[14:15]
	v_pk_fma_f32 v[14:15], v[178:179], v[178:179], v[14:15]
	v_pk_fma_f32 v[14:15], v[180:181], v[180:181], v[14:15]
	v_pk_fma_f32 v[14:15], v[182:183], v[182:183], v[14:15]
	v_pk_fma_f32 v[14:15], v[184:185], v[184:185], v[14:15]
	v_pk_fma_f32 v[14:15], v[186:187], v[186:187], v[14:15]
	v_add_f32_e32 v12, v12, v13
	v_add_f32_e32 v14, v14, v15
	ds_bpermute_b32 v208, v5, v12
	ds_bpermute_b32 v209, v5, v14
	s_waitcnt lgkmcnt(1)
	v_add_f32_e32 v12, v12, v208
	s_waitcnt lgkmcnt(0)
	v_add_f32_e32 v14, v14, v209
	ds_bpermute_b32 v208, v6, v12
	ds_bpermute_b32 v209, v6, v14
	s_waitcnt lgkmcnt(1)
	v_add_f32_e32 v12, v12, v208
	s_waitcnt lgkmcnt(0)
	v_add_f32_e32 v14, v14, v209
	ds_bpermute_b32 v208, v7, v12
	ds_bpermute_b32 v209, v7, v14
	s_waitcnt lgkmcnt(1)
	v_add_f32_e32 v12, v12, v208
	s_waitcnt lgkmcnt(0)
	v_add_f32_e32 v14, v14, v209
	ds_bpermute_b32 v208, v8, v12
	ds_bpermute_b32 v209, v8, v14
	s_waitcnt lgkmcnt(1)
	v_add_f32_e32 v12, v12, v208
	s_waitcnt lgkmcnt(0)
	v_add_f32_e32 v14, v14, v209
	ds_bpermute_b32 v208, v9, v12
	ds_bpermute_b32 v209, v9, v14
	s_waitcnt lgkmcnt(1)
	v_add_f32_e32 v12, v12, v208
	s_waitcnt lgkmcnt(0)
	v_add_f32_e32 v14, v14, v209
	ds_bpermute_b32 v208, v10, v12
	ds_bpermute_b32 v209, v10, v14
	s_waitcnt lgkmcnt(1)
	v_add_f32_e32 v12, v12, v208
	s_waitcnt lgkmcnt(0)
	v_add_f32_e32 v14, v14, v209
	v_fmamk_f32 v16, v12, 0x3a800000, v4
	v_fmamk_f32 v18, v14, 0x3a800000, v4
	v_rsq_f32_e32 v16, v16
	v_rsq_f32_e32 v18, v18
	s_nop 0
	s_mov_b32 s0, s22
	s_lshl_b32 s1, s0, 11
	s_add_u32 s12, s30, 0x8d2000
	s_addc_u32 s13, s31, 0
	s_add_u32 s12, s12, s1
	s_addc_u32 s13, s13, 0
	v_pk_mul_f32 v[196:197], v[156:157], v[16:17] op_sel_hi:[1,0]
	v_pk_mul_f32 v[198:199], v[158:159], v[16:17] op_sel_hi:[1,0]
	v_pk_fma_f32 v[196:197], v[36:37], v[196:197], v[52:53]
	v_pk_fma_f32 v[198:199], v[38:39], v[198:199], v[54:55]
	v_cvt_pk_bf16_f32 v204, v196, v197
	v_cvt_pk_bf16_f32 v205, v198, v199
	global_store_dwordx2 v3, v[204:205], s[12:13]
	v_pk_mul_f32 v[200:201], v[160:161], v[16:17] op_sel_hi:[1,0]
	v_pk_mul_f32 v[202:203], v[162:163], v[16:17] op_sel_hi:[1,0]
	v_pk_fma_f32 v[200:201], v[40:41], v[200:201], v[56:57]
	v_pk_fma_f32 v[202:203], v[42:43], v[202:203], v[58:59]
	v_cvt_pk_bf16_f32 v206, v200, v201
	v_cvt_pk_bf16_f32 v207, v202, v203
	global_store_dwordx2 v3, v[206:207], s[12:13] offset:512
	v_pk_mul_f32 v[196:197], v[164:165], v[16:17] op_sel_hi:[1,0]
	v_pk_mul_f32 v[198:199], v[166:167], v[16:17] op_sel_hi:[1,0]
	v_pk_fma_f32 v[196:197], v[44:45], v[196:197], v[60:61]
	v_pk_fma_f32 v[198:199], v[46:47], v[198:199], v[62:63]
	v_cvt_pk_bf16_f32 v204, v196, v197
	v_cvt_pk_bf16_f32 v205, v198, v199
	global_store_dwordx2 v3, v[204:205], s[12:13] offset:1024
	v_pk_mul_f32 v[200:201], v[168:169], v[16:17] op_sel_hi:[1,0]
	v_pk_mul_f32 v[202:203], v[170:171], v[16:17] op_sel_hi:[1,0]
	v_pk_fma_f32 v[200:201], v[48:49], v[200:201], v[64:65]
	v_pk_fma_f32 v[202:203], v[50:51], v[202:203], v[66:67]
	v_cvt_pk_bf16_f32 v206, v200, v201
	v_cvt_pk_bf16_f32 v207, v202, v203
	global_store_dwordx2 v3, v[206:207], s[12:13] offset:1536
	s_add_u32 s0, s22, 1
	s_lshl_b32 s1, s0, 11
	s_add_u32 s12, s30, 0x8d2000
	s_addc_u32 s13, s31, 0
	s_add_u32 s12, s12, s1
	s_addc_u32 s13, s13, 0
	v_pk_mul_f32 v[196:197], v[172:173], v[18:19] op_sel_hi:[1,0]
	v_pk_mul_f32 v[198:199], v[174:175], v[18:19] op_sel_hi:[1,0]
	v_pk_fma_f32 v[196:197], v[36:37], v[196:197], v[52:53]
	v_pk_fma_f32 v[198:199], v[38:39], v[198:199], v[54:55]
	v_cvt_pk_bf16_f32 v204, v196, v197
	v_cvt_pk_bf16_f32 v205, v198, v199
	global_store_dwordx2 v3, v[204:205], s[12:13]
	v_pk_mul_f32 v[200:201], v[176:177], v[18:19] op_sel_hi:[1,0]
	v_pk_mul_f32 v[202:203], v[178:179], v[18:19] op_sel_hi:[1,0]
	v_pk_fma_f32 v[200:201], v[40:41], v[200:201], v[56:57]
	v_pk_fma_f32 v[202:203], v[42:43], v[202:203], v[58:59]
	v_cvt_pk_bf16_f32 v206, v200, v201
	v_cvt_pk_bf16_f32 v207, v202, v203
	global_store_dwordx2 v3, v[206:207], s[12:13] offset:512
	v_pk_mul_f32 v[196:197], v[180:181], v[18:19] op_sel_hi:[1,0]
	v_pk_mul_f32 v[198:199], v[182:183], v[18:19] op_sel_hi:[1,0]
	v_pk_fma_f32 v[196:197], v[44:45], v[196:197], v[60:61]
	v_pk_fma_f32 v[198:199], v[46:47], v[198:199], v[62:63]
	v_cvt_pk_bf16_f32 v204, v196, v197
	v_cvt_pk_bf16_f32 v205, v198, v199
	global_store_dwordx2 v3, v[204:205], s[12:13] offset:1024
	v_pk_mul_f32 v[200:201], v[184:185], v[18:19] op_sel_hi:[1,0]
	v_pk_mul_f32 v[202:203], v[186:187], v[18:19] op_sel_hi:[1,0]
	v_pk_fma_f32 v[200:201], v[48:49], v[200:201], v[64:65]
	v_pk_fma_f32 v[202:203], v[50:51], v[202:203], v[66:67]
	v_cvt_pk_bf16_f32 v206, v200, v201
	v_cvt_pk_bf16_f32 v207, v202, v203
	global_store_dwordx2 v3, v[206:207], s[12:13] offset:1536
	s_mov_b32 s22, s3
	s_cmp_lt_u32 s22, 0x5000
	s_cbranch_scc1 .Lnm1_top0
.Lnm1_exit:
.LBB0_175:
	s_or_b64 exec, exec, s[4:5]
	s_cmpk_lg_i32 s86, 0x100
	s_cselect_b64 s[80:81], -1, 0
	s_cmpk_eq_i32 s86, 0x100
	s_cselect_b64 s[0:1], -1, 0
	v_writelane_b32 v254, s0, 39
	s_movk_i32 s3, 0x148
	s_waitcnt vmcnt(15)
	v_mov_b32_e32 v0, v195
	v_writelane_b32 v254, s1, 40
	s_and_b64 s[0:1], s[0:1], exec
	s_cselect_b32 s3, s3, 0x3e8
	s_cmp_gt_i32 s2, -1
	s_cselect_b64 s[0:1], -1, 0
	s_cmp_lt_u32 s2, s3
	s_cselect_b64 s[4:5], -1, 0
	s_and_b64 s[0:1], s[0:1], s[4:5]
	s_andn2_b64 vcc, exec, s[0:1]
	s_cbranch_vccnz .LBB0_216
	s_add_u32 s4, s30, 0x800000
	s_addc_u32 s5, s31, 0
	s_add_u32 s20, s30, 0xdf52000
	s_addc_u32 s21, s31, 0
	s_add_u32 s22, s30, 0xdb52000
	v_readlane_b32 s36, v254, 5
	s_addc_u32 s23, s31, 0
	v_readlane_b32 s48, v254, 17
	v_readlane_b32 s49, v254, 18
	s_cmp_eq_u64 s[48:49], 0
	s_cselect_b64 s[6:7], -1, 0
	s_add_u32 s24, s30, 0xd0d2000
	v_lshlrev_b32_e32 v0, 3, v0
	s_addc_u32 s25, s31, 0
	s_lshl_b32 s0, s2, 7
	v_readlane_b32 s37, v254, 6
	v_readlane_b32 s38, v254, 7
	v_readlane_b32 s39, v254, 8
	v_readlane_b32 s40, v254, 9
	v_readlane_b32 s41, v254, 10
	v_readlane_b32 s42, v254, 11
	v_readlane_b32 s43, v254, 12
	v_readlane_b32 s44, v254, 13
	v_readlane_b32 s45, v254, 14
	s_sub_i32 s26, s0, 32
	v_lshl_add_u32 v0, s2, 12, v0
	s_lshl_b32 s0, s2, 2
	s_lshl_b32 s27, s86, 7
	s_waitcnt vmcnt(7)
	v_add_u32_e32 v32, 0xffc38000, v0
	s_lshl_b32 s36, s86, 12
	s_lshl_b32 s37, s2, 4
	s_lshl_b32 s38, s86, 4
	s_add_i32 s39, s0, 0xfffff8e0
	s_lshl_b32 s40, s86, 2
	s_mov_b32 s9, 0
	v_mov_b32_e32 v35, 0
	s_mov_b64 s[10:11], 0x40000
	s_mov_b32 s41, 0x40000
	s_movk_i32 s42, 0x84
	s_mov_b64 s[12:13], 0x100000
	s_mov_b32 s43, 0x100000
	s_movk_i32 s44, 0x5080
	s_mov_b32 s45, s2
	v_readlane_b32 s46, v254, 15
	v_readlane_b32 s47, v254, 16
	v_readlane_b32 s50, v254, 19
	v_readlane_b32 s51, v254, 20
	s_branch .LBB0_179

.LBB0_1043:
	s_or_b64 exec, exec, s[0:1]
	s_waitcnt lgkmcnt(0)
	v_mov_b32_e32 v0, v195
	s_barrier
	s_lshl_b32 s57, s2, 4
	s_lshl_b32 s56, s86, 4
	v_and_b32_e32 v0, 63, v195
	v_lshlrev_b32_e32 v2, 4, v0
	v_lshlrev_b32_e32 v3, 3, v0
	v_xor_b32_e32 v5, 1, v0
	v_lshlrev_b32_e32 v5, 2, v5
	v_xor_b32_e32 v6, 2, v0
	v_lshlrev_b32_e32 v6, 2, v6
	v_xor_b32_e32 v7, 4, v0
	v_lshlrev_b32_e32 v7, 2, v7
	v_xor_b32_e32 v8, 8, v0
	v_lshlrev_b32_e32 v8, 2, v8
	v_xor_b32_e32 v9, 16, v0
	v_lshlrev_b32_e32 v9, 2, v9
	v_xor_b32_e32 v10, 32, v0
	v_lshlrev_b32_e32 v10, 2, v10
	v_mov_b32_e32 v4, 0x358637bd
	v_readfirstlane_b32 s0, v195
	s_nop 1
	s_lshr_b32 s0, s0, 6
	s_lshl_b32 s1, s2, 3
	s_add_u32 s0, s0, s1
	s_mul_i32 s22, s0, 2
	s_mul_i32 s23, s86, 16
	s_cmp_lt_u32 s22, 0x4000
	s_cbranch_scc0 .Lnm6a_exit
	v_readlane_b32 s4, v254, 29
	v_readlane_b32 s5, v254, 30
	s_nop 7
	global_load_dwordx4 v[20:23], v2, s[4:5]
	global_load_dwordx4 v[24:27], v2, s[4:5] offset:1024
	global_load_dwordx4 v[28:31], v2, s[4:5] offset:2048
	global_load_dwordx4 v[32:35], v2, s[4:5] offset:3072
	s_mov_b32 s0, s22
	s_cmp_lt_u32 s0, 0x1000
	s_cselect_b32 s10, s52, s54
	s_cselect_b32 s11, s53, s55
	s_cselect_b32 s1, 0, 0x1000
	s_sub_u32 s1, s0, s1
	s_lshl_b32 s1, s1, 12
	s_add_u32 s10, s10, s1
	s_addc_u32 s11, s11, 0
	global_load_dwordx4 v[124:127], v2, s[10:11] nt
	global_load_dwordx4 v[128:131], v2, s[10:11] offset:1024 nt
	global_load_dwordx4 v[132:135], v2, s[10:11] offset:2048 nt
	global_load_dwordx4 v[136:139], v2, s[10:11] offset:3072 nt
	s_lshl_b32 s1, s0, 11
	s_add_u32 s12, s30, 0x8d2000
	s_addc_u32 s13, s31, 0
	s_add_u32 s12, s12, s1
	s_addc_u32 s13, s13, 0
	global_load_dwordx2 v[196:197], v3, s[12:13]
	global_load_dwordx2 v[198:199], v3, s[12:13] offset:512
	global_load_dwordx2 v[200:201], v3, s[12:13] offset:1024
	global_load_dwordx2 v[202:203], v3, s[12:13] offset:1536
	s_add_u32 s0, s22, 1
	s_cmp_lt_u32 s0, 0x1000
	s_cselect_b32 s10, s52, s54
	s_cselect_b32 s11, s53, s55
	s_cselect_b32 s1, 0, 0x1000
	s_sub_u32 s1, s0, s1
	s_lshl_b32 s1, s1, 12
	s_add_u32 s10, s10, s1
	s_addc_u32 s11, s11, 0
	global_load_dwordx4 v[140:143], v2, s[10:11] nt
	global_load_dwordx4 v[144:147], v2, s[10:11] offset:1024 nt
	global_load_dwordx4 v[148:151], v2, s[10:11] offset:2048 nt
	global_load_dwordx4 v[152:155], v2, s[10:11] offset:3072 nt
	s_lshl_b32 s1, s0, 11
	s_add_u32 s12, s30, 0x8d2000
	s_addc_u32 s13, s31, 0
	s_add_u32 s12, s12, s1
	s_addc_u32 s13, s13, 0
	global_load_dwordx2 v[204:205], v3, s[12:13]
	global_load_dwordx2 v[206:207], v3, s[12:13] offset:512
	global_load_dwordx2 v[208:209], v3, s[12:13] offset:1024
	global_load_dwordx2 v[210:211], v3, s[12:13] offset:1536
	s_sub_u32 s1, s22, 0x1000
	s_lshr_b32 s1, s1, 12
	s_add_u32 s1, s1, 1
	s_cmp_lt_u32 s22, 0x1000
	s_cselect_b32 s1, 0, s1
	s_mul_i32 s1, s1, 0x6000
	s_add_u32 s14, s30, 0x843000
	s_addc_u32 s15, s31, 0
	s_add_u32 s14, s14, s1
	s_addc_u32 s15, s15, 0
	s_add_u32 s16, s14, 0x1000
	s_addc_u32 s17, s15, 0
	global_load_dwordx4 v[84:87], v2, s[14:15]
	global_load_dwordx4 v[88:91], v2, s[14:15] offset:1024
	global_load_dwordx4 v[92:95], v2, s[14:15] offset:2048
	global_load_dwordx4 v[96:99], v2, s[14:15] offset:3072
	global_load_dwordx4 v[68:71], v2, s[16:17]
	global_load_dwordx4 v[72:75], v2, s[16:17] offset:1024
	global_load_dwordx4 v[76:79], v2, s[16:17] offset:2048
	global_load_dwordx4 v[80:83], v2, s[16:17] offset:3072
	s_add_u32 s18, s30, 0x85e000
	s_addc_u32 s19, s31, 0
	s_bfe_u32 s1, s22, 0x60006
	s_lshl_b32 s1, s1, 11
	s_add_u32 s20, s18, s1
	s_addc_u32 s21, s19, 0
	global_load_dwordx4 v[100:103], v2, s[20:21]
	global_load_dwordx4 v[104:107], v2, s[20:21] offset:1024
	s_and_b32 s1, s22, 63
	s_lshl_b32 s1, s1, 11
	s_add_u32 s20, s18, s1
	s_addc_u32 s21, s19, 0
	global_load_dwordx4 v[108:111], v2, s[20:21]
	global_load_dwordx4 v[112:115], v2, s[20:21] offset:1024
	global_load_dwordx4 v[116:119], v2, s[20:21] offset:2048
	global_load_dwordx4 v[120:123], v2, s[20:21] offset:3072
	s_waitcnt vmcnt(0)
	s_branch .Lnm6a_go0
.Lnm6a_top0:
	s_waitcnt vmcnt(16)

.Lnm6a_nope0:
	s_add_u32 s3, s22, s23
	s_cmp_lt_u32 s3, 0x4000
	s_cbranch_scc0 .Lnm6a_nopf0
	s_mov_b32 s0, s3
	s_cmp_lt_u32 s0, 0x1000
	s_cselect_b32 s10, s52, s54
	s_cselect_b32 s11, s53, s55
	s_cselect_b32 s1, 0, 0x1000
	s_sub_u32 s1, s0, s1
	s_lshl_b32 s1, s1, 12
	s_add_u32 s10, s10, s1
	s_addc_u32 s11, s11, 0
	global_load_dwordx4 v[156:159], v2, s[10:11] nt
	global_load_dwordx4 v[160:163], v2, s[10:11] offset:1024 nt
	global_load_dwordx4 v[164:167], v2, s[10:11] offset:2048 nt
	global_load_dwordx4 v[168:171], v2, s[10:11] offset:3072 nt
	s_lshl_b32 s1, s0, 11
	s_add_u32 s12, s30, 0x8d2000
	s_addc_u32 s13, s31, 0
	s_add_u32 s12, s12, s1
	s_addc_u32 s13, s13, 0
	global_load_dwordx2 v[212:213], v3, s[12:13]
	global_load_dwordx2 v[214:215], v3, s[12:13] offset:512
	global_load_dwordx2 v[216:217], v3, s[12:13] offset:1024
	global_load_dwordx2 v[218:219], v3, s[12:13] offset:1536
	s_add_u32 s0, s3, 1
	s_cmp_lt_u32 s0, 0x1000
	s_cselect_b32 s10, s52, s54
	s_cselect_b32 s11, s53, s55
	s_cselect_b32 s1, 0, 0x1000
	s_sub_u32 s1, s0, s1
	s_lshl_b32 s1, s1, 12
	s_add_u32 s10, s10, s1
	s_addc_u32 s11, s11, 0
	global_load_dwordx4 v[172:175], v2, s[10:11] nt
	global_load_dwordx4 v[176:179], v2, s[10:11] offset:1024 nt
	global_load_dwordx4 v[180:183], v2, s[10:11] offset:2048 nt
	global_load_dwordx4 v[184:187], v2, s[10:11] offset:3072 nt
	s_lshl_b32 s1, s0, 11
	s_add_u32 s12, s30, 0x8d2000
	s_addc_u32 s13, s31, 0
	s_add_u32 s12, s12, s1
	s_addc_u32 s13, s13, 0
	global_load_dwordx2 v[220:221], v3, s[12:13]
	global_load_dwordx2 v[222:223], v3, s[12:13] offset:512
	global_load_dwordx2 v[224:225], v3, s[12:13] offset:1024
	global_load_dwordx2 v[226:227], v3, s[12:13] offset:1536
	s_sub_u32 s1, s3, 0x1000
	s_lshr_b32 s1, s1, 12
	s_add_u32 s1, s1, 1
	s_cmp_lt_u32 s3, 0x1000
	s_cselect_b32 s1, 0, s1
	s_mul_i32 s1, s1, 0x6000
	s_add_u32 s14, s30, 0x843000
	s_addc_u32 s15, s31, 0
	s_add_u32 s14, s14, s1
	s_addc_u32 s15, s15, 0
	s_add_u32 s16, s14, 0x1000
	s_addc_u32 s17, s15, 0
	global_load_dwordx4 v[84:87], v2, s[14:15]
	global_load_dwordx4 v[88:91], v2, s[14:15] offset:1024
	global_load_dwordx4 v[92:95], v2, s[14:15] offset:2048
	global_load_dwordx4 v[96:99], v2, s[14:15] offset:3072
	global_load_dwordx4 v[68:71], v2, s[16:17]
	global_load_dwordx4 v[72:75], v2, s[16:17] offset:1024
	global_load_dwordx4 v[76:79], v2, s[16:17] offset:2048
	global_load_dwordx4 v[80:83], v2, s[16:17] offset:3072
	s_add_u32 s18, s30, 0x85e000
	s_addc_u32 s19, s31, 0
	s_bfe_u32 s1, s3, 0x60006
	s_lshl_b32 s1, s1, 11
	s_add_u32 s20, s18, s1
	s_addc_u32 s21, s19, 0
	global_load_dwordx4 v[100:103], v2, s[20:21]
	global_load_dwordx4 v[104:107], v2, s[20:21] offset:1024
	s_and_b32 s1, s3, 63
	s_lshl_b32 s1, s1, 11
	s_add_u32 s20, s18, s1
	s_addc_u32 s21, s19, 0
	global_load_dwordx4 v[108:111], v2, s[20:21]
	global_load_dwordx4 v[112:115], v2, s[20:21] offset:1024
	global_load_dwordx4 v[116:119], v2, s[20:21] offset:2048
	global_load_dwordx4 v[120:123], v2, s[20:21] offset:3072
.Lnm6a_nopf0:
	s_mov_b32 s0, s22
	s_lshl_b32 s1, s0, 12
	s_add_u32 s10, s28, s1
	s_addc_u32 s11, s29, 0
	v_lshlrev_b32_e32 v228, 16, v196
	v_and_b32_e32 v229, 0xffff0000, v196
	v_lshlrev_b32_e32 v230, 16, v197
	v_and_b32_e32 v231, 0xffff0000, v197
	v_pk_add_f32 v[124:125], v[124:125], v[228:229]
	v_pk_add_f32 v[126:127], v[126:127], v[230:231]
	v_cvt_pk_bf16_f32 v236, v124, v125
	v_cvt_pk_bf16_f32 v237, v126, v127
	global_store_dwordx2 v3, v[236:237], s[10:11]
	v_pk_mul_f32 v[12:13], v[124:125], v[124:125]
	v_pk_fma_f32 v[12:13], v[126:127], v[126:127], v[12:13]
	v_lshlrev_b32_e32 v232, 16, v198
	v_and_b32_e32 v233, 0xffff0000, v198
	v_lshlrev_b32_e32 v234, 16, v199
	v_and_b32_e32 v235, 0xffff0000, v199
	v_pk_add_f32 v[128:129], v[128:129], v[232:233]
	v_pk_add_f32 v[130:131], v[130:131], v[234:235]
	v_cvt_pk_bf16_f32 v238, v128, v129
	v_cvt_pk_bf16_f32 v239, v130, v131
	global_store_dwordx2 v3, v[238:239], s[10:11] offset:512
	v_pk_fma_f32 v[12:13], v[128:129], v[128:129], v[12:13]
	v_pk_fma_f32 v[12:13], v[130:131], v[130:131], v[12:13]
	v_lshlrev_b32_e32 v228, 16, v200
	v_and_b32_e32 v229, 0xffff0000, v200
	v_lshlrev_b32_e32 v230, 16, v201
	v_and_b32_e32 v231, 0xffff0000, v201
	v_pk_add_f32 v[132:133], v[132:133], v[228:229]
	v_pk_add_f32 v[134:135], v[134:135], v[230:231]
	v_cvt_pk_bf16_f32 v236, v132, v133
	v_cvt_pk_bf16_f32 v237, v134, v135
	global_store_dwordx2 v3, v[236:237], s[10:11] offset:1024
	v_pk_fma_f32 v[12:13], v[132:133], v[132:133], v[12:13]
	v_pk_fma_f32 v[12:13], v[134:135], v[134:135], v[12:13]
	v_lshlrev_b32_e32 v232, 16, v202
	v_and_b32_e32 v233, 0xffff0000, v202
	v_lshlrev_b32_e32 v234, 16, v203
	v_and_b32_e32 v235, 0xffff0000, v203
	v_pk_add_f32 v[136:137], v[136:137], v[232:233]
	v_pk_add_f32 v[138:139], v[138:139], v[234:235]
	v_cvt_pk_bf16_f32 v238, v136, v137
	v_cvt_pk_bf16_f32 v239, v138, v139
	global_store_dwordx2 v3, v[238:239], s[10:11] offset:1536
	v_pk_fma_f32 v[12:13], v[136:137], v[136:137], v[12:13]
	v_pk_fma_f32 v[12:13], v[138:139], v[138:139], v[12:13]
	s_add_u32 s0, s22, 1
	s_lshl_b32 s1, s0, 12
	s_add_u32 s10, s28, s1
	s_addc_u32 s11, s29, 0
	v_lshlrev_b32_e32 v228, 16, v204
	v_and_b32_e32 v229, 0xffff0000, v204
	v_lshlrev_b32_e32 v230, 16, v205
	v_and_b32_e32 v231, 0xffff0000, v205
	v_pk_add_f32 v[140:141], v[140:141], v[228:229]
	v_pk_add_f32 v[142:143], v[142:143], v[230:231]
	v_cvt_pk_bf16_f32 v236, v140, v141
	v_cvt_pk_bf16_f32 v237, v142, v143
	global_store_dwordx2 v3, v[236:237], s[10:11]
	v_pk_mul_f32 v[14:15], v[140:141], v[140:141]
	v_pk_fma_f32 v[14:15], v[142:143], v[142:143], v[14:15]
	v_lshlrev_b32_e32 v232, 16, v206
	v_and_b32_e32 v233, 0xffff0000, v206
	v_lshlrev_b32_e32 v234, 16, v207
	v_and_b32_e32 v235, 0xffff0000, v207
	v_pk_add_f32 v[144:145], v[144:145], v[232:233]
	v_pk_add_f32 v[146:147], v[146:147], v[234:235]
	v_cvt_pk_bf16_f32 v238, v144, v145
	v_cvt_pk_bf16_f32 v239, v146, v147
	global_store_dwordx2 v3, v[238:239], s[10:11] offset:512
	v_pk_fma_f32 v[14:15], v[144:145], v[144:145], v[14:15]
	v_pk_fma_f32 v[14:15], v[146:147], v[146:147], v[14:15]
	v_lshlrev_b32_e32 v228, 16, v208
	v_and_b32_e32 v229, 0xffff0000, v208
	v_lshlrev_b32_e32 v230, 16, v209
	v_and_b32_e32 v231, 0xffff0000, v209
	v_pk_add_f32 v[148:149], v[148:149], v[228:229]
	v_pk_add_f32 v[150:151], v[150:151], v[230:231]
	v_cvt_pk_bf16_f32 v236, v148, v149
	v_cvt_pk_bf16_f32 v237, v150, v151
	global_store_dwordx2 v3, v[236:237], s[10:11] offset:1024
	v_pk_fma_f32 v[14:15], v[148:149], v[148:149], v[14:15]
	v_pk_fma_f32 v[14:15], v[150:151], v[150:151], v[14:15]
	v_lshlrev_b32_e32 v232, 16, v210
	v_and_b32_e32 v233, 0xffff0000, v210
	v_lshlrev_b32_e32 v234, 16, v211
	v_and_b32_e32 v235, 0xffff0000, v211
	v_pk_add_f32 v[152:153], v[152:153], v[232:233]
	v_pk_add_f32 v[154:155], v[154:155], v[234:235]
	v_cvt_pk_bf16_f32 v238, v152, v153
	v_cvt_pk_bf16_f32 v239, v154, v155
	global_store_dwordx2 v3, v[238:239], s[10:11] offset:1536
	v_pk_fma_f32 v[14:15], v[152:153], v[152:153], v[14:15]
	v_pk_fma_f32 v[14:15], v[154:155], v[154:155], v[14:15]
	v_add_f32_e32 v12, v12, v13
	v_add_f32_e32 v14, v14, v15
	ds_bpermute_b32 v240, v5, v12
	ds_bpermute_b32 v241, v5, v14
	s_waitcnt lgkmcnt(1)
	v_add_f32_e32 v12, v12, v240
	s_waitcnt lgkmcnt(0)
	v_add_f32_e32 v14, v14, v241
	ds_bpermute_b32 v240, v6, v12
	ds_bpermute_b32 v241, v6, v14
	s_waitcnt lgkmcnt(1)
	v_add_f32_e32 v12, v12, v240
	s_waitcnt lgkmcnt(0)
	v_add_f32_e32 v14, v14, v241
	ds_bpermute_b32 v240, v7, v12
	ds_bpermute_b32 v241, v7, v14
	s_waitcnt lgkmcnt(1)
	v_add_f32_e32 v12, v12, v240
	s_waitcnt lgkmcnt(0)
	v_add_f32_e32 v14, v14, v241
	ds_bpermute_b32 v240, v8, v12
	ds_bpermute_b32 v241, v8, v14
	s_waitcnt lgkmcnt(1)
	v_add_f32_e32 v12, v12, v240
	s_waitcnt lgkmcnt(0)
	v_add_f32_e32 v14, v14, v241
	ds_bpermute_b32 v240, v9, v12
	ds_bpermute_b32 v241, v9, v14
	s_waitcnt lgkmcnt(1)
	v_add_f32_e32 v12, v12, v240
	s_waitcnt lgkmcnt(0)
	v_add_f32_e32 v14, v14, v241
	ds_bpermute_b32 v240, v10, v12
	ds_bpermute_b32 v241, v10, v14
	s_waitcnt lgkmcnt(1)
	v_add_f32_e32 v12, v12, v240
	s_waitcnt lgkmcnt(0)
	v_add_f32_e32 v14, v14, v241
	v_fmamk_f32 v16, v12, 0x3a800000, v4
	v_fmamk_f32 v18, v14, 0x3a800000, v4
	v_rsq_f32_e32 v16, v16
	v_rsq_f32_e32 v18, v18
	s_nop 0
	s_mov_b32 s0, s22
	s_lshl_b32 s1, s0, 11
	s_add_u32 s12, s30, 0x8d2000
	s_addc_u32 s13, s31, 0
	s_add_u32 s12, s12, s1
	s_addc_u32 s13, s13, 0
	v_pk_mul_f32 v[228:229], v[124:125], v[16:17] op_sel_hi:[1,0]
	v_pk_mul_f32 v[230:231], v[126:127], v[16:17] op_sel_hi:[1,0]
	v_pk_fma_f32 v[228:229], v[36:37], v[228:229], v[52:53]
	v_pk_fma_f32 v[230:231], v[38:39], v[230:231], v[54:55]
	v_cvt_pk_bf16_f32 v236, v228, v229
	v_cvt_pk_bf16_f32 v237, v230, v231
	global_store_dwordx2 v3, v[236:237], s[12:13]
	v_pk_mul_f32 v[232:233], v[128:129], v[16:17] op_sel_hi:[1,0]
	v_pk_mul_f32 v[234:235], v[130:131], v[16:17] op_sel_hi:[1,0]
	v_pk_fma_f32 v[232:233], v[40:41], v[232:233], v[56:57]
	v_pk_fma_f32 v[234:235], v[42:43], v[234:235], v[58:59]
	v_cvt_pk_bf16_f32 v238, v232, v233
	v_cvt_pk_bf16_f32 v239, v234, v235
	global_store_dwordx2 v3, v[238:239], s[12:13] offset:512
	v_pk_mul_f32 v[228:229], v[132:133], v[16:17] op_sel_hi:[1,0]
	v_pk_mul_f32 v[230:231], v[134:135], v[16:17] op_sel_hi:[1,0]
	v_pk_fma_f32 v[228:229], v[44:45], v[228:229], v[60:61]
	v_pk_fma_f32 v[230:231], v[46:47], v[230:231], v[62:63]
	v_cvt_pk_bf16_f32 v236, v228, v229
	v_cvt_pk_bf16_f32 v237, v230, v231
	global_store_dwordx2 v3, v[236:237], s[12:13] offset:1024
	v_pk_mul_f32 v[232:233], v[136:137], v[16:17] op_sel_hi:[1,0]
	v_pk_mul_f32 v[234:235], v[138:139], v[16:17] op_sel_hi:[1,0]
	v_pk_fma_f32 v[232:233], v[48:49], v[232:233], v[64:65]
	v_pk_fma_f32 v[234:235], v[50:51], v[234:235], v[66:67]
	v_cvt_pk_bf16_f32 v238, v232, v233
	v_cvt_pk_bf16_f32 v239, v234, v235
	global_store_dwordx2 v3, v[238:239], s[12:13] offset:1536
	s_add_u32 s0, s22, 1
	s_lshl_b32 s1, s0, 11
	s_add_u32 s12, s30, 0x8d2000
	s_addc_u32 s13, s31, 0
	s_add_u32 s12, s12, s1
	s_addc_u32 s13, s13, 0
	v_pk_mul_f32 v[228:229], v[140:141], v[18:19] op_sel_hi:[1,0]
	v_pk_mul_f32 v[230:231], v[142:143], v[18:19] op_sel_hi:[1,0]
	v_pk_fma_f32 v[228:229], v[36:37], v[228:229], v[52:53]
	v_pk_fma_f32 v[230:231], v[38:39], v[230:231], v[54:55]
	v_cvt_pk_bf16_f32 v236, v228, v229
	v_cvt_pk_bf16_f32 v237, v230, v231
	global_store_dwordx2 v3, v[236:237], s[12:13]
	v_pk_mul_f32 v[232:233], v[144:145], v[18:19] op_sel_hi:[1,0]
	v_pk_mul_f32 v[234:235], v[146:147], v[18:19] op_sel_hi:[1,0]
	v_pk_fma_f32 v[232:233], v[40:41], v[232:233], v[56:57]
	v_pk_fma_f32 v[234:235], v[42:43], v[234:235], v[58:59]
	v_cvt_pk_bf16_f32 v238, v232, v233
	v_cvt_pk_bf16_f32 v239, v234, v235
	global_store_dwordx2 v3, v[238:239], s[12:13] offset:512
	v_pk_mul_f32 v[228:229], v[148:149], v[18:19] op_sel_hi:[1,0]
	v_pk_mul_f32 v[230:231], v[150:151], v[18:19] op_sel_hi:[1,0]
	v_pk_fma_f32 v[228:229], v[44:45], v[228:229], v[60:61]
	v_pk_fma_f32 v[230:231], v[46:47], v[230:231], v[62:63]
	v_cvt_pk_bf16_f32 v236, v228, v229
	v_cvt_pk_bf16_f32 v237, v230, v231
	global_store_dwordx2 v3, v[236:237], s[12:13] offset:1024
	v_pk_mul_f32 v[232:233], v[152:153], v[18:19] op_sel_hi:[1,0]
	v_pk_mul_f32 v[234:235], v[154:155], v[18:19] op_sel_hi:[1,0]
	v_pk_fma_f32 v[232:233], v[48:49], v[232:233], v[64:65]
	v_pk_fma_f32 v[234:235], v[50:51], v[234:235], v[66:67]
	v_cvt_pk_bf16_f32 v238, v232, v233
	v_cvt_pk_bf16_f32 v239, v234, v235
	global_store_dwordx2 v3, v[238:239], s[12:13] offset:1536
	s_mov_b32 s22, s3
	s_cmp_lt_u32 s22, 0x4000
	s_cbranch_scc0 .Lnm6a_exit

.Lnm6a_nope1:
	s_add_u32 s3, s22, s23
	s_cmp_lt_u32 s3, 0x4000
	s_cbranch_scc0 .Lnm6a_nopf1
	s_mov_b32 s0, s3
	s_cmp_lt_u32 s0, 0x1000
	s_cselect_b32 s10, s52, s54
	s_cselect_b32 s11, s53, s55
	s_cselect_b32 s1, 0, 0x1000
	s_sub_u32 s1, s0, s1
	s_lshl_b32 s1, s1, 12
	s_add_u32 s10, s10, s1
	s_addc_u32 s11, s11, 0
	global_load_dwordx4 v[124:127], v2, s[10:11] nt
	global_load_dwordx4 v[128:131], v2, s[10:11] offset:1024 nt
	global_load_dwordx4 v[132:135], v2, s[10:11] offset:2048 nt
	global_load_dwordx4 v[136:139], v2, s[10:11] offset:3072 nt
	s_lshl_b32 s1, s0, 11
	s_add_u32 s12, s30, 0x8d2000
	s_addc_u32 s13, s31, 0
	s_add_u32 s12, s12, s1
	s_addc_u32 s13, s13, 0
	global_load_dwordx2 v[196:197], v3, s[12:13]
	global_load_dwordx2 v[198:199], v3, s[12:13] offset:512
	global_load_dwordx2 v[200:201], v3, s[12:13] offset:1024
	global_load_dwordx2 v[202:203], v3, s[12:13] offset:1536
	s_add_u32 s0, s3, 1
	s_cmp_lt_u32 s0, 0x1000
	s_cselect_b32 s10, s52, s54
	s_cselect_b32 s11, s53, s55
	s_cselect_b32 s1, 0, 0x1000
	s_sub_u32 s1, s0, s1
	s_lshl_b32 s1, s1, 12
	s_add_u32 s10, s10, s1
	s_addc_u32 s11, s11, 0
	global_load_dwordx4 v[140:143], v2, s[10:11] nt
	global_load_dwordx4 v[144:147], v2, s[10:11] offset:1024 nt
	global_load_dwordx4 v[148:151], v2, s[10:11] offset:2048 nt
	global_load_dwordx4 v[152:155], v2, s[10:11] offset:3072 nt
	s_lshl_b32 s1, s0, 11
	s_add_u32 s12, s30, 0x8d2000
	s_addc_u32 s13, s31, 0
	s_add_u32 s12, s12, s1
	s_addc_u32 s13, s13, 0
	global_load_dwordx2 v[204:205], v3, s[12:13]
	global_load_dwordx2 v[206:207], v3, s[12:13] offset:512
	global_load_dwordx2 v[208:209], v3, s[12:13] offset:1024
	global_load_dwordx2 v[210:211], v3, s[12:13] offset:1536
	s_sub_u32 s1, s3, 0x1000
	s_lshr_b32 s1, s1, 12
	s_add_u32 s1, s1, 1
	s_cmp_lt_u32 s3, 0x1000
	s_cselect_b32 s1, 0, s1
	s_mul_i32 s1, s1, 0x6000
	s_add_u32 s14, s30, 0x843000
	s_addc_u32 s15, s31, 0
	s_add_u32 s14, s14, s1
	s_addc_u32 s15, s15, 0
	s_add_u32 s16, s14, 0x1000
	s_addc_u32 s17, s15, 0
	global_load_dwordx4 v[84:87], v2, s[14:15]
	global_load_dwordx4 v[88:91], v2, s[14:15] offset:1024
	global_load_dwordx4 v[92:95], v2, s[14:15] offset:2048
	global_load_dwordx4 v[96:99], v2, s[14:15] offset:3072
	global_load_dwordx4 v[68:71], v2, s[16:17]
	global_load_dwordx4 v[72:75], v2, s[16:17] offset:1024
	global_load_dwordx4 v[76:79], v2, s[16:17] offset:2048
	global_load_dwordx4 v[80:83], v2, s[16:17] offset:3072
	s_add_u32 s18, s30, 0x85e000
	s_addc_u32 s19, s31, 0
	s_bfe_u32 s1, s3, 0x60006
	s_lshl_b32 s1, s1, 11
	s_add_u32 s20, s18, s1
	s_addc_u32 s21, s19, 0
	global_load_dwordx4 v[100:103], v2, s[20:21]
	global_load_dwordx4 v[104:107], v2, s[20:21] offset:1024
	s_and_b32 s1, s3, 63
	s_lshl_b32 s1, s1, 11
	s_add_u32 s20, s18, s1
	s_addc_u32 s21, s19, 0
	global_load_dwordx4 v[108:111], v2, s[20:21]
	global_load_dwordx4 v[112:115], v2, s[20:21] offset:1024
	global_load_dwordx4 v[116:119], v2, s[20:21] offset:2048
	global_load_dwordx4 v[120:123], v2, s[20:21] offset:3072
.Lnm6a_nopf1:
	s_mov_b32 s0, s22
	s_lshl_b32 s1, s0, 12
	s_add_u32 s10, s28, s1
	s_addc_u32 s11, s29, 0
	v_lshlrev_b32_e32 v228, 16, v212
	v_and_b32_e32 v229, 0xffff0000, v212
	v_lshlrev_b32_e32 v230, 16, v213
	v_and_b32_e32 v231, 0xffff0000, v213
	v_pk_add_f32 v[156:157], v[156:157], v[228:229]
	v_pk_add_f32 v[158:159], v[158:159], v[230:231]
	v_cvt_pk_bf16_f32 v236, v156, v157
	v_cvt_pk_bf16_f32 v237, v158, v159
	global_store_dwordx2 v3, v[236:237], s[10:11]
	v_pk_mul_f32 v[12:13], v[156:157], v[156:157]
	v_pk_fma_f32 v[12:13], v[158:159], v[158:159], v[12:13]
	v_lshlrev_b32_e32 v232, 16, v214
	v_and_b32_e32 v233, 0xffff0000, v214
	v_lshlrev_b32_e32 v234, 16, v215
	v_and_b32_e32 v235, 0xffff0000, v215
	v_pk_add_f32 v[160:161], v[160:161], v[232:233]
	v_pk_add_f32 v[162:163], v[162:163], v[234:235]
	v_cvt_pk_bf16_f32 v238, v160, v161
	v_cvt_pk_bf16_f32 v239, v162, v163
	global_store_dwordx2 v3, v[238:239], s[10:11] offset:512
	v_pk_fma_f32 v[12:13], v[160:161], v[160:161], v[12:13]
	v_pk_fma_f32 v[12:13], v[162:163], v[162:163], v[12:13]
	v_lshlrev_b32_e32 v228, 16, v216
	v_and_b32_e32 v229, 0xffff0000, v216
	v_lshlrev_b32_e32 v230, 16, v217
	v_and_b32_e32 v231, 0xffff0000, v217
	v_pk_add_f32 v[164:165], v[164:165], v[228:229]
	v_pk_add_f32 v[166:167], v[166:167], v[230:231]
	v_cvt_pk_bf16_f32 v236, v164, v165
	v_cvt_pk_bf16_f32 v237, v166, v167
	global_store_dwordx2 v3, v[236:237], s[10:11] offset:1024
	v_pk_fma_f32 v[12:13], v[164:165], v[164:165], v[12:13]
	v_pk_fma_f32 v[12:13], v[166:167], v[166:167], v[12:13]
	v_lshlrev_b32_e32 v232, 16, v218
	v_and_b32_e32 v233, 0xffff0000, v218
	v_lshlrev_b32_e32 v234, 16, v219
	v_and_b32_e32 v235, 0xffff0000, v219
	v_pk_add_f32 v[168:169], v[168:169], v[232:233]
	v_pk_add_f32 v[170:171], v[170:171], v[234:235]
	v_cvt_pk_bf16_f32 v238, v168, v169
	v_cvt_pk_bf16_f32 v239, v170, v171
	global_store_dwordx2 v3, v[238:239], s[10:11] offset:1536
	v_pk_fma_f32 v[12:13], v[168:169], v[168:169], v[12:13]
	v_pk_fma_f32 v[12:13], v[170:171], v[170:171], v[12:13]
	s_add_u32 s0, s22, 1
	s_lshl_b32 s1, s0, 12
	s_add_u32 s10, s28, s1
	s_addc_u32 s11, s29, 0
	v_lshlrev_b32_e32 v228, 16, v220
	v_and_b32_e32 v229, 0xffff0000, v220
	v_lshlrev_b32_e32 v230, 16, v221
	v_and_b32_e32 v231, 0xffff0000, v221
	v_pk_add_f32 v[172:173], v[172:173], v[228:229]
	v_pk_add_f32 v[174:175], v[174:175], v[230:231]
	v_cvt_pk_bf16_f32 v236, v172, v173
	v_cvt_pk_bf16_f32 v237, v174, v175
	global_store_dwordx2 v3, v[236:237], s[10:11]
	v_pk_mul_f32 v[14:15], v[172:173], v[172:173]
	v_pk_fma_f32 v[14:15], v[174:175], v[174:175], v[14:15]
	v_lshlrev_b32_e32 v232, 16, v222
	v_and_b32_e32 v233, 0xffff0000, v222
	v_lshlrev_b32_e32 v234, 16, v223
	v_and_b32_e32 v235, 0xffff0000, v223
	v_pk_add_f32 v[176:177], v[176:177], v[232:233]
	v_pk_add_f32 v[178:179], v[178:179], v[234:235]
	v_cvt_pk_bf16_f32 v238, v176, v177
	v_cvt_pk_bf16_f32 v239, v178, v179
	global_store_dwordx2 v3, v[238:239], s[10:11] offset:512
	v_pk_fma_f32 v[14:15], v[176:177], v[176:177], v[14:15]
	v_pk_fma_f32 v[14:15], v[178:179], v[178:179], v[14:15]
	v_lshlrev_b32_e32 v228, 16, v224
	v_and_b32_e32 v229, 0xffff0000, v224
	v_lshlrev_b32_e32 v230, 16, v225
	v_and_b32_e32 v231, 0xffff0000, v225
	v_pk_add_f32 v[180:181], v[180:181], v[228:229]
	v_pk_add_f32 v[182:183], v[182:183], v[230:231]
	v_cvt_pk_bf16_f32 v236, v180, v181
	v_cvt_pk_bf16_f32 v237, v182, v183
	global_store_dwordx2 v3, v[236:237], s[10:11] offset:1024
	v_pk_fma_f32 v[14:15], v[180:181], v[180:181], v[14:15]
	v_pk_fma_f32 v[14:15], v[182:183], v[182:183], v[14:15]
	v_lshlrev_b32_e32 v232, 16, v226
	v_and_b32_e32 v233, 0xffff0000, v226
	v_lshlrev_b32_e32 v234, 16, v227
	v_and_b32_e32 v235, 0xffff0000, v227
	v_pk_add_f32 v[184:185], v[184:185], v[232:233]
	v_pk_add_f32 v[186:187], v[186:187], v[234:235]
	v_cvt_pk_bf16_f32 v238, v184, v185
	v_cvt_pk_bf16_f32 v239, v186, v187
	global_store_dwordx2 v3, v[238:239], s[10:11] offset:1536
	v_pk_fma_f32 v[14:15], v[184:185], v[184:185], v[14:15]
	v_pk_fma_f32 v[14:15], v[186:187], v[186:187], v[14:15]
	v_add_f32_e32 v12, v12, v13
	v_add_f32_e32 v14, v14, v15
	ds_bpermute_b32 v240, v5, v12
	ds_bpermute_b32 v241, v5, v14
	s_waitcnt lgkmcnt(1)
	v_add_f32_e32 v12, v12, v240
	s_waitcnt lgkmcnt(0)
	v_add_f32_e32 v14, v14, v241
	ds_bpermute_b32 v240, v6, v12
	ds_bpermute_b32 v241, v6, v14
	s_waitcnt lgkmcnt(1)
	v_add_f32_e32 v12, v12, v240
	s_waitcnt lgkmcnt(0)
	v_add_f32_e32 v14, v14, v241
	ds_bpermute_b32 v240, v7, v12
	ds_bpermute_b32 v241, v7, v14
	s_waitcnt lgkmcnt(1)
	v_add_f32_e32 v12, v12, v240
	s_waitcnt lgkmcnt(0)
	v_add_f32_e32 v14, v14, v241
	ds_bpermute_b32 v240, v8, v12
	ds_bpermute_b32 v241, v8, v14
	s_waitcnt lgkmcnt(1)
	v_add_f32_e32 v12, v12, v240
	s_waitcnt lgkmcnt(0)
	v_add_f32_e32 v14, v14, v241
	ds_bpermute_b32 v240, v9, v12
	ds_bpermute_b32 v241, v9, v14
	s_waitcnt lgkmcnt(1)
	v_add_f32_e32 v12, v12, v240
	s_waitcnt lgkmcnt(0)
	v_add_f32_e32 v14, v14, v241
	ds_bpermute_b32 v240, v10, v12
	ds_bpermute_b32 v241, v10, v14
	s_waitcnt lgkmcnt(1)
	v_add_f32_e32 v12, v12, v240
	s_waitcnt lgkmcnt(0)
	v_add_f32_e32 v14, v14, v241
	v_fmamk_f32 v16, v12, 0x3a800000, v4
	v_fmamk_f32 v18, v14, 0x3a800000, v4
	v_rsq_f32_e32 v16, v16
	v_rsq_f32_e32 v18, v18
	s_nop 0
	s_mov_b32 s0, s22
	s_lshl_b32 s1, s0, 11
	s_add_u32 s12, s30, 0x8d2000
	s_addc_u32 s13, s31, 0
	s_add_u32 s12, s12, s1
	s_addc_u32 s13, s13, 0
	v_pk_mul_f32 v[228:229], v[156:157], v[16:17] op_sel_hi:[1,0]
	v_pk_mul_f32 v[230:231], v[158:159], v[16:17] op_sel_hi:[1,0]
	v_pk_fma_f32 v[228:229], v[36:37], v[228:229], v[52:53]
	v_pk_fma_f32 v[230:231], v[38:39], v[230:231], v[54:55]
	v_cvt_pk_bf16_f32 v236, v228, v229
	v_cvt_pk_bf16_f32 v237, v230, v231
	global_store_dwordx2 v3, v[236:237], s[12:13]
	v_pk_mul_f32 v[232:233], v[160:161], v[16:17] op_sel_hi:[1,0]
	v_pk_mul_f32 v[234:235], v[162:163], v[16:17] op_sel_hi:[1,0]
	v_pk_fma_f32 v[232:233], v[40:41], v[232:233], v[56:57]
	v_pk_fma_f32 v[234:235], v[42:43], v[234:235], v[58:59]
	v_cvt_pk_bf16_f32 v238, v232, v233
	v_cvt_pk_bf16_f32 v239, v234, v235
	global_store_dwordx2 v3, v[238:239], s[12:13] offset:512
	v_pk_mul_f32 v[228:229], v[164:165], v[16:17] op_sel_hi:[1,0]
	v_pk_mul_f32 v[230:231], v[166:167], v[16:17] op_sel_hi:[1,0]
	v_pk_fma_f32 v[228:229], v[44:45], v[228:229], v[60:61]
	v_pk_fma_f32 v[230:231], v[46:47], v[230:231], v[62:63]
	v_cvt_pk_bf16_f32 v236, v228, v229
	v_cvt_pk_bf16_f32 v237, v230, v231
	global_store_dwordx2 v3, v[236:237], s[12:13] offset:1024
	v_pk_mul_f32 v[232:233], v[168:169], v[16:17] op_sel_hi:[1,0]
	v_pk_mul_f32 v[234:235], v[170:171], v[16:17] op_sel_hi:[1,0]
	v_pk_fma_f32 v[232:233], v[48:49], v[232:233], v[64:65]
	v_pk_fma_f32 v[234:235], v[50:51], v[234:235], v[66:67]
	v_cvt_pk_bf16_f32 v238, v232, v233
	v_cvt_pk_bf16_f32 v239, v234, v235
	global_store_dwordx2 v3, v[238:239], s[12:13] offset:1536
	s_add_u32 s0, s22, 1
	s_lshl_b32 s1, s0, 11
	s_add_u32 s12, s30, 0x8d2000
	s_addc_u32 s13, s31, 0
	s_add_u32 s12, s12, s1
	s_addc_u32 s13, s13, 0
	v_pk_mul_f32 v[228:229], v[172:173], v[18:19] op_sel_hi:[1,0]
	v_pk_mul_f32 v[230:231], v[174:175], v[18:19] op_sel_hi:[1,0]
	v_pk_fma_f32 v[228:229], v[36:37], v[228:229], v[52:53]
	v_pk_fma_f32 v[230:231], v[38:39], v[230:231], v[54:55]
	v_cvt_pk_bf16_f32 v236, v228, v229
	v_cvt_pk_bf16_f32 v237, v230, v231
	global_store_dwordx2 v3, v[236:237], s[12:13]
	v_pk_mul_f32 v[232:233], v[176:177], v[18:19] op_sel_hi:[1,0]
	v_pk_mul_f32 v[234:235], v[178:179], v[18:19] op_sel_hi:[1,0]
	v_pk_fma_f32 v[232:233], v[40:41], v[232:233], v[56:57]
	v_pk_fma_f32 v[234:235], v[42:43], v[234:235], v[58:59]
	v_cvt_pk_bf16_f32 v238, v232, v233
	v_cvt_pk_bf16_f32 v239, v234, v235
	global_store_dwordx2 v3, v[238:239], s[12:13] offset:512
	v_pk_mul_f32 v[228:229], v[180:181], v[18:19] op_sel_hi:[1,0]
	v_pk_mul_f32 v[230:231], v[182:183], v[18:19] op_sel_hi:[1,0]
	v_pk_fma_f32 v[228:229], v[44:45], v[228:229], v[60:61]
	v_pk_fma_f32 v[230:231], v[46:47], v[230:231], v[62:63]
	v_cvt_pk_bf16_f32 v236, v228, v229
	v_cvt_pk_bf16_f32 v237, v230, v231
	global_store_dwordx2 v3, v[236:237], s[12:13] offset:1024
	v_pk_mul_f32 v[232:233], v[184:185], v[18:19] op_sel_hi:[1,0]
	v_pk_mul_f32 v[234:235], v[186:187], v[18:19] op_sel_hi:[1,0]
	v_pk_fma_f32 v[232:233], v[48:49], v[232:233], v[64:65]
	v_pk_fma_f32 v[234:235], v[50:51], v[234:235], v[66:67]
	v_cvt_pk_bf16_f32 v238, v232, v233
	v_cvt_pk_bf16_f32 v239, v234, v235
	global_store_dwordx2 v3, v[238:239], s[12:13] offset:1536
	s_mov_b32 s22, s3
	s_cmp_lt_u32 s22, 0x4000
	s_cbranch_scc1 .Lnm6a_top0
.Lnm6a_exit:
	v_and_b32_e32 v0, 63, v195
	v_lshlrev_b32_e32 v2, 4, v0
	v_lshlrev_b32_e32 v3, 3, v0
	v_xor_b32_e32 v5, 1, v0
	v_lshlrev_b32_e32 v5, 2, v5
	v_xor_b32_e32 v6, 2, v0
	v_lshlrev_b32_e32 v6, 2, v6
	v_xor_b32_e32 v7, 4, v0
	v_lshlrev_b32_e32 v7, 2, v7
	v_xor_b32_e32 v8, 8, v0
	v_lshlrev_b32_e32 v8, 2, v8
	v_xor_b32_e32 v9, 16, v0
	v_lshlrev_b32_e32 v9, 2, v9
	v_xor_b32_e32 v10, 32, v0
	v_lshlrev_b32_e32 v10, 2, v10
	v_mov_b32_e32 v4, 0x358637bd
	v_readfirstlane_b32 s0, v195
	s_nop 1
	s_lshr_b32 s0, s0, 6
	s_lshl_b32 s1, s2, 3
	s_add_u32 s0, s0, s1
	s_mul_i32 s22, s0, 1
	s_add_u32 s22, s22, 0x4000
	s_mul_i32 s23, s86, 8
	s_cmp_lt_u32 s22, 0x5000
	s_cbranch_scc0 .Lnm6b_exit
	v_readlane_b32 s4, v254, 29
	v_readlane_b32 s5, v254, 30
	s_nop 7
	global_load_dwordx4 v[20:23], v2, s[4:5]
	global_load_dwordx4 v[24:27], v2, s[4:5] offset:1024
	global_load_dwordx4 v[28:31], v2, s[4:5] offset:2048
	global_load_dwordx4 v[32:35], v2, s[4:5] offset:3072
	s_mov_b32 s0, s22
	s_cmp_lt_u32 s0, 0x1000
	s_cselect_b32 s10, s52, s54
	s_cselect_b32 s11, s53, s55
	s_cselect_b32 s1, 0, 0x1000
	s_sub_u32 s1, s0, s1
	s_lshl_b32 s1, s1, 12
	s_add_u32 s10, s10, s1
	s_addc_u32 s11, s11, 0
	global_load_dwordx4 v[196:199], v2, s[10:11] nt
	global_load_dwordx4 v[200:203], v2, s[10:11] offset:1024 nt
	global_load_dwordx4 v[204:207], v2, s[10:11] offset:2048 nt
	global_load_dwordx4 v[208:211], v2, s[10:11] offset:3072 nt
	s_lshl_b32 s1, s0, 11
	s_add_u32 s12, s30, 0x8d2000
	s_addc_u32 s13, s31, 0
	s_add_u32 s12, s12, s1
	s_addc_u32 s13, s13, 0
	global_load_dwordx2 v[124:125], v3, s[12:13]
	global_load_dwordx2 v[126:127], v3, s[12:13] offset:512
	global_load_dwordx2 v[128:129], v3, s[12:13] offset:1024
	global_load_dwordx2 v[130:131], v3, s[12:13] offset:1536
	s_add_i32 s1, s0, -16384
	s_lshl_b32 s1, s1, 11
	s_add_u32 s12, s30, 0x30d2000
	s_addc_u32 s13, s31, 0
	s_add_u32 s12, s12, s1
	s_addc_u32 s13, s13, 0
	global_load_dwordx2 v[132:133], v3, s[12:13]
	global_load_dwordx2 v[134:135], v3, s[12:13] offset:512
	global_load_dwordx2 v[136:137], v3, s[12:13] offset:1024
	global_load_dwordx2 v[138:139], v3, s[12:13] offset:1536
	s_add_i32 s1, s0, -12288
	s_lshl_b32 s1, s1, 11
	s_add_u32 s12, s30, 0x30d2000
	s_addc_u32 s13, s31, 0
	s_add_u32 s12, s12, s1
	s_addc_u32 s13, s13, 0
	global_load_dwordx2 v[140:141], v3, s[12:13]
	global_load_dwordx2 v[142:143], v3, s[12:13] offset:512
	global_load_dwordx2 v[144:145], v3, s[12:13] offset:1024
	global_load_dwordx2 v[146:147], v3, s[12:13] offset:1536
	s_add_i32 s1, s0, -8192
	s_lshl_b32 s1, s1, 11
	s_add_u32 s12, s30, 0x30d2000
	s_addc_u32 s13, s31, 0
	s_add_u32 s12, s12, s1
	s_addc_u32 s13, s13, 0
	global_load_dwordx2 v[148:149], v3, s[12:13]
	global_load_dwordx2 v[150:151], v3, s[12:13] offset:512
	global_load_dwordx2 v[152:153], v3, s[12:13] offset:1024
	global_load_dwordx2 v[154:155], v3, s[12:13] offset:1536
	s_sub_u32 s1, s22, 0x1000
	s_lshr_b32 s1, s1, 12
	s_add_u32 s1, s1, 1
	s_cmp_lt_u32 s22, 0x1000
	s_cselect_b32 s1, 0, s1
	s_mul_i32 s1, s1, 0x6000
	s_add_u32 s14, s30, 0x843000
	s_addc_u32 s15, s31, 0
	s_add_u32 s14, s14, s1
	s_addc_u32 s15, s15, 0
	s_add_u32 s16, s14, 0x1000
	s_addc_u32 s17, s15, 0
	global_load_dwordx4 v[84:87], v2, s[14:15]
	global_load_dwordx4 v[88:91], v2, s[14:15] offset:1024
	global_load_dwordx4 v[92:95], v2, s[14:15] offset:2048
	global_load_dwordx4 v[96:99], v2, s[14:15] offset:3072
	global_load_dwordx4 v[68:71], v2, s[16:17]
	global_load_dwordx4 v[72:75], v2, s[16:17] offset:1024
	global_load_dwordx4 v[76:79], v2, s[16:17] offset:2048
	global_load_dwordx4 v[80:83], v2, s[16:17] offset:3072
	s_add_u32 s18, s30, 0x85e000
	s_addc_u32 s19, s31, 0
	s_bfe_u32 s1, s22, 0x60006
	s_lshl_b32 s1, s1, 11
	s_add_u32 s20, s18, s1
	s_addc_u32 s21, s19, 0
	global_load_dwordx4 v[100:103], v2, s[20:21]
	global_load_dwordx4 v[104:107], v2, s[20:21] offset:1024
	s_and_b32 s1, s22, 63
	s_lshl_b32 s1, s1, 11
	s_add_u32 s20, s18, s1
	s_addc_u32 s21, s19, 0
	global_load_dwordx4 v[108:111], v2, s[20:21]
	global_load_dwordx4 v[112:115], v2, s[20:21] offset:1024
	s_waitcnt vmcnt(0)
	s_branch .Lnm6b_go0

.Lnm6b_go0:
	v_pk_add_f32 v[36:37], v[68:69], 1.0 op_sel_hi:[1,0]
	v_pk_add_f32 v[38:39], v[70:71], 1.0 op_sel_hi:[1,0]
	v_pk_add_f32 v[40:41], v[72:73], 1.0 op_sel_hi:[1,0]
	v_pk_add_f32 v[42:43], v[74:75], 1.0 op_sel_hi:[1,0]
	v_pk_add_f32 v[44:45], v[76:77], 1.0 op_sel_hi:[1,0]
	v_pk_add_f32 v[46:47], v[78:79], 1.0 op_sel_hi:[1,0]
	v_pk_add_f32 v[48:49], v[80:81], 1.0 op_sel_hi:[1,0]
	v_pk_add_f32 v[50:51], v[82:83], 1.0 op_sel_hi:[1,0]
	v_pk_mul_f32 v[36:37], v[20:21], v[36:37]
	v_pk_mul_f32 v[38:39], v[22:23], v[38:39]
	v_pk_mul_f32 v[40:41], v[24:25], v[40:41]
	v_pk_mul_f32 v[42:43], v[26:27], v[42:43]
	v_pk_mul_f32 v[44:45], v[28:29], v[44:45]
	v_pk_mul_f32 v[46:47], v[30:31], v[46:47]
	v_pk_mul_f32 v[48:49], v[32:33], v[48:49]
	v_pk_mul_f32 v[50:51], v[34:35], v[50:51]
	v_mov_b32_e32 v52, v84
	v_mov_b32_e32 v53, v85
	v_mov_b32_e32 v54, v86
	v_mov_b32_e32 v55, v87
	v_mov_b32_e32 v56, v88
	v_mov_b32_e32 v57, v89
	v_mov_b32_e32 v58, v90
	v_mov_b32_e32 v59, v91
	v_mov_b32_e32 v60, v92
	v_mov_b32_e32 v61, v93
	v_mov_b32_e32 v62, v94
	v_mov_b32_e32 v63, v95
	v_mov_b32_e32 v64, v96
	v_mov_b32_e32 v65, v97
	v_mov_b32_e32 v66, v98
	v_mov_b32_e32 v67, v99
	s_cmp_lt_u32 s22, 0x1000
	s_cbranch_scc1 .Lnm6b_nope0
	v_pk_add_f32 v[196:197], v[196:197], v[100:101]
	v_pk_add_f32 v[198:199], v[198:199], v[102:103]
	v_pk_add_f32 v[200:201], v[200:201], v[104:105]
	v_pk_add_f32 v[202:203], v[202:203], v[106:107]
	v_pk_add_f32 v[204:205], v[204:205], v[108:109]
	v_pk_add_f32 v[206:207], v[206:207], v[110:111]
	v_pk_add_f32 v[208:209], v[208:209], v[112:113]
	v_pk_add_f32 v[210:211], v[210:211], v[114:115]
.Lnm6b_nope0:
	s_add_u32 s3, s22, s23
	s_cmp_lt_u32 s3, 0x5000
	s_cbranch_scc0 .Lnm6b_nopf0
	s_mov_b32 s0, s3
	s_cmp_lt_u32 s0, 0x1000
	s_cselect_b32 s10, s52, s54
	s_cselect_b32 s11, s53, s55
	s_cselect_b32 s1, 0, 0x1000
	s_sub_u32 s1, s0, s1
	s_lshl_b32 s1, s1, 12
	s_add_u32 s10, s10, s1
	s_addc_u32 s11, s11, 0
	global_load_dwordx4 v[212:215], v2, s[10:11] nt
	global_load_dwordx4 v[216:219], v2, s[10:11] offset:1024 nt
	global_load_dwordx4 v[220:223], v2, s[10:11] offset:2048 nt
	global_load_dwordx4 v[224:227], v2, s[10:11] offset:3072 nt
	s_lshl_b32 s1, s0, 11
	s_add_u32 s12, s30, 0x8d2000
	s_addc_u32 s13, s31, 0
	s_add_u32 s12, s12, s1
	s_addc_u32 s13, s13, 0
	global_load_dwordx2 v[156:157], v3, s[12:13]
	global_load_dwordx2 v[158:159], v3, s[12:13] offset:512
	global_load_dwordx2 v[160:161], v3, s[12:13] offset:1024
	global_load_dwordx2 v[162:163], v3, s[12:13] offset:1536
	s_add_i32 s1, s0, -16384
	s_lshl_b32 s1, s1, 11
	s_add_u32 s12, s30, 0x30d2000
	s_addc_u32 s13, s31, 0
	s_add_u32 s12, s12, s1
	s_addc_u32 s13, s13, 0
	global_load_dwordx2 v[164:165], v3, s[12:13]
	global_load_dwordx2 v[166:167], v3, s[12:13] offset:512
	global_load_dwordx2 v[168:169], v3, s[12:13] offset:1024
	global_load_dwordx2 v[170:171], v3, s[12:13] offset:1536
	s_add_i32 s1, s0, -12288
	s_lshl_b32 s1, s1, 11
	s_add_u32 s12, s30, 0x30d2000
	s_addc_u32 s13, s31, 0
	s_add_u32 s12, s12, s1
	s_addc_u32 s13, s13, 0
	global_load_dwordx2 v[172:173], v3, s[12:13]
	global_load_dwordx2 v[174:175], v3, s[12:13] offset:512
	global_load_dwordx2 v[176:177], v3, s[12:13] offset:1024
	global_load_dwordx2 v[178:179], v3, s[12:13] offset:1536
	s_add_i32 s1, s0, -8192
	s_lshl_b32 s1, s1, 11
	s_add_u32 s12, s30, 0x30d2000
	s_addc_u32 s13, s31, 0
	s_add_u32 s12, s12, s1
	s_addc_u32 s13, s13, 0
	global_load_dwordx2 v[180:181], v3, s[12:13]
	global_load_dwordx2 v[182:183], v3, s[12:13] offset:512
	global_load_dwordx2 v[184:185], v3, s[12:13] offset:1024
	global_load_dwordx2 v[186:187], v3, s[12:13] offset:1536
	s_sub_u32 s1, s3, 0x1000
	s_lshr_b32 s1, s1, 12
	s_add_u32 s1, s1, 1
	s_cmp_lt_u32 s3, 0x1000
	s_cselect_b32 s1, 0, s1
	s_mul_i32 s1, s1, 0x6000
	s_add_u32 s14, s30, 0x843000
	s_addc_u32 s15, s31, 0
	s_add_u32 s14, s14, s1
	s_addc_u32 s15, s15, 0
	s_add_u32 s16, s14, 0x1000
	s_addc_u32 s17, s15, 0
	global_load_dwordx4 v[84:87], v2, s[14:15]
	global_load_dwordx4 v[88:91], v2, s[14:15] offset:1024
	global_load_dwordx4 v[92:95], v2, s[14:15] offset:2048
	global_load_dwordx4 v[96:99], v2, s[14:15] offset:3072
	global_load_dwordx4 v[68:71], v2, s[16:17]
	global_load_dwordx4 v[72:75], v2, s[16:17] offset:1024
	global_load_dwordx4 v[76:79], v2, s[16:17] offset:2048
	global_load_dwordx4 v[80:83], v2, s[16:17] offset:3072
	s_add_u32 s18, s30, 0x85e000
	s_addc_u32 s19, s31, 0
	s_bfe_u32 s1, s3, 0x60006
	s_lshl_b32 s1, s1, 11
	s_add_u32 s20, s18, s1
	s_addc_u32 s21, s19, 0
	global_load_dwordx4 v[100:103], v2, s[20:21]
	global_load_dwordx4 v[104:107], v2, s[20:21] offset:1024
	s_and_b32 s1, s3, 63
	s_lshl_b32 s1, s1, 11
	s_add_u32 s20, s18, s1
	s_addc_u32 s21, s19, 0
	global_load_dwordx4 v[108:111], v2, s[20:21]
	global_load_dwordx4 v[112:115], v2, s[20:21] offset:1024
.Lnm6b_nopf0:
	s_mov_b32 s0, s22
	s_lshl_b32 s1, s0, 12
	s_add_u32 s10, s28, s1
	s_addc_u32 s11, s29, 0
	v_lshlrev_b32_e32 v228, 16, v124
	v_and_b32_e32 v229, 0xffff0000, v124
	v_lshlrev_b32_e32 v230, 16, v125
	v_and_b32_e32 v231, 0xffff0000, v125
	v_pk_add_f32 v[196:197], v[196:197], v[228:229]
	v_pk_add_f32 v[198:199], v[198:199], v[230:231]
	v_lshlrev_b32_e32 v232, 16, v132
	v_and_b32_e32 v233, 0xffff0000, v132
	v_lshlrev_b32_e32 v234, 16, v133
	v_and_b32_e32 v235, 0xffff0000, v133
	v_pk_add_f32 v[196:197], v[196:197], v[232:233]
	v_pk_add_f32 v[198:199], v[198:199], v[234:235]
	v_lshlrev_b32_e32 v228, 16, v140
	v_and_b32_e32 v229, 0xffff0000, v140
	v_lshlrev_b32_e32 v230, 16, v141
	v_and_b32_e32 v231, 0xffff0000, v141
	v_pk_add_f32 v[196:197], v[196:197], v[228:229]
	v_pk_add_f32 v[198:199], v[198:199], v[230:231]
	v_lshlrev_b32_e32 v232, 16, v148
	v_and_b32_e32 v233, 0xffff0000, v148
	v_lshlrev_b32_e32 v234, 16, v149
	v_and_b32_e32 v235, 0xffff0000, v149
	v_pk_add_f32 v[196:197], v[196:197], v[232:233]
	v_pk_add_f32 v[198:199], v[198:199], v[234:235]
	v_cvt_pk_bf16_f32 v236, v196, v197
	v_cvt_pk_bf16_f32 v237, v198, v199
	global_store_dwordx2 v3, v[236:237], s[10:11]
	v_pk_mul_f32 v[12:13], v[196:197], v[196:197]
	v_pk_fma_f32 v[12:13], v[198:199], v[198:199], v[12:13]
	v_lshlrev_b32_e32 v228, 16, v126
	v_and_b32_e32 v229, 0xffff0000, v126
	v_lshlrev_b32_e32 v230, 16, v127
	v_and_b32_e32 v231, 0xffff0000, v127
	v_pk_add_f32 v[200:201], v[200:201], v[228:229]
	v_pk_add_f32 v[202:203], v[202:203], v[230:231]
	v_lshlrev_b32_e32 v232, 16, v134
	v_and_b32_e32 v233, 0xffff0000, v134
	v_lshlrev_b32_e32 v234, 16, v135
	v_and_b32_e32 v235, 0xffff0000, v135
	v_pk_add_f32 v[200:201], v[200:201], v[232:233]
	v_pk_add_f32 v[202:203], v[202:203], v[234:235]
	v_lshlrev_b32_e32 v228, 16, v142
	v_and_b32_e32 v229, 0xffff0000, v142
	v_lshlrev_b32_e32 v230, 16, v143
	v_and_b32_e32 v231, 0xffff0000, v143
	v_pk_add_f32 v[200:201], v[200:201], v[228:229]
	v_pk_add_f32 v[202:203], v[202:203], v[230:231]
	v_lshlrev_b32_e32 v232, 16, v150
	v_and_b32_e32 v233, 0xffff0000, v150
	v_lshlrev_b32_e32 v234, 16, v151
	v_and_b32_e32 v235, 0xffff0000, v151
	v_pk_add_f32 v[200:201], v[200:201], v[232:233]
	v_pk_add_f32 v[202:203], v[202:203], v[234:235]
	v_cvt_pk_bf16_f32 v238, v200, v201
	v_cvt_pk_bf16_f32 v239, v202, v203
	global_store_dwordx2 v3, v[238:239], s[10:11] offset:512
	v_pk_fma_f32 v[12:13], v[200:201], v[200:201], v[12:13]
	v_pk_fma_f32 v[12:13], v[202:203], v[202:203], v[12:13]
	v_lshlrev_b32_e32 v228, 16, v128
	v_and_b32_e32 v229, 0xffff0000, v128
	v_lshlrev_b32_e32 v230, 16, v129
	v_and_b32_e32 v231, 0xffff0000, v129
	v_pk_add_f32 v[204:205], v[204:205], v[228:229]
	v_pk_add_f32 v[206:207], v[206:207], v[230:231]
	v_lshlrev_b32_e32 v232, 16, v136
	v_and_b32_e32 v233, 0xffff0000, v136
	v_lshlrev_b32_e32 v234, 16, v137
	v_and_b32_e32 v235, 0xffff0000, v137
	v_pk_add_f32 v[204:205], v[204:205], v[232:233]
	v_pk_add_f32 v[206:207], v[206:207], v[234:235]
	v_lshlrev_b32_e32 v228, 16, v144
	v_and_b32_e32 v229, 0xffff0000, v144
	v_lshlrev_b32_e32 v230, 16, v145
	v_and_b32_e32 v231, 0xffff0000, v145
	v_pk_add_f32 v[204:205], v[204:205], v[228:229]
	v_pk_add_f32 v[206:207], v[206:207], v[230:231]
	v_lshlrev_b32_e32 v232, 16, v152
	v_and_b32_e32 v233, 0xffff0000, v152
	v_lshlrev_b32_e32 v234, 16, v153
	v_and_b32_e32 v235, 0xffff0000, v153
	v_pk_add_f32 v[204:205], v[204:205], v[232:233]
	v_pk_add_f32 v[206:207], v[206:207], v[234:235]
	v_cvt_pk_bf16_f32 v236, v204, v205
	v_cvt_pk_bf16_f32 v237, v206, v207
	global_store_dwordx2 v3, v[236:237], s[10:11] offset:1024
	v_pk_fma_f32 v[12:13], v[204:205], v[204:205], v[12:13]
	v_pk_fma_f32 v[12:13], v[206:207], v[206:207], v[12:13]
	v_lshlrev_b32_e32 v228, 16, v130
	v_and_b32_e32 v229, 0xffff0000, v130
	v_lshlrev_b32_e32 v230, 16, v131
	v_and_b32_e32 v231, 0xffff0000, v131
	v_pk_add_f32 v[208:209], v[208:209], v[228:229]
	v_pk_add_f32 v[210:211], v[210:211], v[230:231]
	v_lshlrev_b32_e32 v232, 16, v138
	v_and_b32_e32 v233, 0xffff0000, v138
	v_lshlrev_b32_e32 v234, 16, v139
	v_and_b32_e32 v235, 0xffff0000, v139
	v_pk_add_f32 v[208:209], v[208:209], v[232:233]
	v_pk_add_f32 v[210:211], v[210:211], v[234:235]
	v_lshlrev_b32_e32 v228, 16, v146
	v_and_b32_e32 v229, 0xffff0000, v146
	v_lshlrev_b32_e32 v230, 16, v147
	v_and_b32_e32 v231, 0xffff0000, v147
	v_pk_add_f32 v[208:209], v[208:209], v[228:229]
	v_pk_add_f32 v[210:211], v[210:211], v[230:231]
	v_lshlrev_b32_e32 v232, 16, v154
	v_and_b32_e32 v233, 0xffff0000, v154
	v_lshlrev_b32_e32 v234, 16, v155
	v_and_b32_e32 v235, 0xffff0000, v155
	v_pk_add_f32 v[208:209], v[208:209], v[232:233]
	v_pk_add_f32 v[210:211], v[210:211], v[234:235]
	v_cvt_pk_bf16_f32 v238, v208, v209
	v_cvt_pk_bf16_f32 v239, v210, v211
	global_store_dwordx2 v3, v[238:239], s[10:11] offset:1536
	v_pk_fma_f32 v[12:13], v[208:209], v[208:209], v[12:13]
	v_pk_fma_f32 v[12:13], v[210:211], v[210:211], v[12:13]
	v_add_f32_e32 v12, v12, v13
	ds_bpermute_b32 v240, v5, v12
	s_waitcnt lgkmcnt(0)
	v_add_f32_e32 v12, v12, v240
	ds_bpermute_b32 v240, v6, v12
	s_waitcnt lgkmcnt(0)
	v_add_f32_e32 v12, v12, v240
	ds_bpermute_b32 v240, v7, v12
	s_waitcnt lgkmcnt(0)
	v_add_f32_e32 v12, v12, v240
	ds_bpermute_b32 v240, v8, v12
	s_waitcnt lgkmcnt(0)
	v_add_f32_e32 v12, v12, v240
	ds_bpermute_b32 v240, v9, v12
	s_waitcnt lgkmcnt(0)
	v_add_f32_e32 v12, v12, v240
	ds_bpermute_b32 v240, v10, v12
	s_waitcnt lgkmcnt(0)
	v_add_f32_e32 v12, v12, v240
	v_fmamk_f32 v16, v12, 0x3a800000, v4
	v_rsq_f32_e32 v16, v16
	s_nop 0
	s_mov_b32 s0, s22
	s_lshl_b32 s1, s0, 11
	s_add_u32 s12, s30, 0x8d2000
	s_addc_u32 s13, s31, 0
	s_add_u32 s12, s12, s1
	s_addc_u32 s13, s13, 0
	v_pk_mul_f32 v[228:229], v[196:197], v[16:17] op_sel_hi:[1,0]
	v_pk_mul_f32 v[230:231], v[198:199], v[16:17] op_sel_hi:[1,0]
	v_pk_fma_f32 v[228:229], v[36:37], v[228:229], v[52:53]
	v_pk_fma_f32 v[230:231], v[38:39], v[230:231], v[54:55]
	v_cvt_pk_bf16_f32 v236, v228, v229
	v_cvt_pk_bf16_f32 v237, v230, v231
	global_store_dwordx2 v3, v[236:237], s[12:13]
	v_pk_mul_f32 v[232:233], v[200:201], v[16:17] op_sel_hi:[1,0]
	v_pk_mul_f32 v[234:235], v[202:203], v[16:17] op_sel_hi:[1,0]
	v_pk_fma_f32 v[232:233], v[40:41], v[232:233], v[56:57]
	v_pk_fma_f32 v[234:235], v[42:43], v[234:235], v[58:59]
	v_cvt_pk_bf16_f32 v238, v232, v233
	v_cvt_pk_bf16_f32 v239, v234, v235
	global_store_dwordx2 v3, v[238:239], s[12:13] offset:512
	v_pk_mul_f32 v[228:229], v[204:205], v[16:17] op_sel_hi:[1,0]
	v_pk_mul_f32 v[230:231], v[206:207], v[16:17] op_sel_hi:[1,0]
	v_pk_fma_f32 v[228:229], v[44:45], v[228:229], v[60:61]
	v_pk_fma_f32 v[230:231], v[46:47], v[230:231], v[62:63]
	v_cvt_pk_bf16_f32 v236, v228, v229
	v_cvt_pk_bf16_f32 v237, v230, v231
	global_store_dwordx2 v3, v[236:237], s[12:13] offset:1024
	v_pk_mul_f32 v[232:233], v[208:209], v[16:17] op_sel_hi:[1,0]
	v_pk_mul_f32 v[234:235], v[210:211], v[16:17] op_sel_hi:[1,0]
	v_pk_fma_f32 v[232:233], v[48:49], v[232:233], v[64:65]
	v_pk_fma_f32 v[234:235], v[50:51], v[234:235], v[66:67]
	v_cvt_pk_bf16_f32 v238, v232, v233
	v_cvt_pk_bf16_f32 v239, v234, v235
	global_store_dwordx2 v3, v[238:239], s[12:13] offset:1536
	s_mov_b32 s22, s3
	s_cmp_lt_u32 s22, 0x5000
	s_cbranch_scc0 .Lnm6b_exit

.Lnm6b_go1:
	v_pk_add_f32 v[36:37], v[68:69], 1.0 op_sel_hi:[1,0]
	v_pk_add_f32 v[38:39], v[70:71], 1.0 op_sel_hi:[1,0]
	v_pk_add_f32 v[40:41], v[72:73], 1.0 op_sel_hi:[1,0]
	v_pk_add_f32 v[42:43], v[74:75], 1.0 op_sel_hi:[1,0]
	v_pk_add_f32 v[44:45], v[76:77], 1.0 op_sel_hi:[1,0]
	v_pk_add_f32 v[46:47], v[78:79], 1.0 op_sel_hi:[1,0]
	v_pk_add_f32 v[48:49], v[80:81], 1.0 op_sel_hi:[1,0]
	v_pk_add_f32 v[50:51], v[82:83], 1.0 op_sel_hi:[1,0]
	v_pk_mul_f32 v[36:37], v[20:21], v[36:37]
	v_pk_mul_f32 v[38:39], v[22:23], v[38:39]
	v_pk_mul_f32 v[40:41], v[24:25], v[40:41]
	v_pk_mul_f32 v[42:43], v[26:27], v[42:43]
	v_pk_mul_f32 v[44:45], v[28:29], v[44:45]
	v_pk_mul_f32 v[46:47], v[30:31], v[46:47]
	v_pk_mul_f32 v[48:49], v[32:33], v[48:49]
	v_pk_mul_f32 v[50:51], v[34:35], v[50:51]
	v_mov_b32_e32 v52, v84
	v_mov_b32_e32 v53, v85
	v_mov_b32_e32 v54, v86
	v_mov_b32_e32 v55, v87
	v_mov_b32_e32 v56, v88
	v_mov_b32_e32 v57, v89
	v_mov_b32_e32 v58, v90
	v_mov_b32_e32 v59, v91
	v_mov_b32_e32 v60, v92
	v_mov_b32_e32 v61, v93
	v_mov_b32_e32 v62, v94
	v_mov_b32_e32 v63, v95
	v_mov_b32_e32 v64, v96
	v_mov_b32_e32 v65, v97
	v_mov_b32_e32 v66, v98
	v_mov_b32_e32 v67, v99
	s_cmp_lt_u32 s22, 0x1000
	s_cbranch_scc1 .Lnm6b_nope1
	v_pk_add_f32 v[212:213], v[212:213], v[100:101]
	v_pk_add_f32 v[214:215], v[214:215], v[102:103]
	v_pk_add_f32 v[216:217], v[216:217], v[104:105]
	v_pk_add_f32 v[218:219], v[218:219], v[106:107]
	v_pk_add_f32 v[220:221], v[220:221], v[108:109]
	v_pk_add_f32 v[222:223], v[222:223], v[110:111]
	v_pk_add_f32 v[224:225], v[224:225], v[112:113]
	v_pk_add_f32 v[226:227], v[226:227], v[114:115]
.Lnm6b_nope1:
	s_add_u32 s3, s22, s23
	s_cmp_lt_u32 s3, 0x5000
	s_cbranch_scc0 .Lnm6b_nopf1
	s_mov_b32 s0, s3
	s_cmp_lt_u32 s0, 0x1000
	s_cselect_b32 s10, s52, s54
	s_cselect_b32 s11, s53, s55
	s_cselect_b32 s1, 0, 0x1000
	s_sub_u32 s1, s0, s1
	s_lshl_b32 s1, s1, 12
	s_add_u32 s10, s10, s1
	s_addc_u32 s11, s11, 0
	global_load_dwordx4 v[196:199], v2, s[10:11] nt
	global_load_dwordx4 v[200:203], v2, s[10:11] offset:1024 nt
	global_load_dwordx4 v[204:207], v2, s[10:11] offset:2048 nt
	global_load_dwordx4 v[208:211], v2, s[10:11] offset:3072 nt
	s_lshl_b32 s1, s0, 11
	s_add_u32 s12, s30, 0x8d2000
	s_addc_u32 s13, s31, 0
	s_add_u32 s12, s12, s1
	s_addc_u32 s13, s13, 0
	global_load_dwordx2 v[124:125], v3, s[12:13]
	global_load_dwordx2 v[126:127], v3, s[12:13] offset:512
	global_load_dwordx2 v[128:129], v3, s[12:13] offset:1024
	global_load_dwordx2 v[130:131], v3, s[12:13] offset:1536
	s_add_i32 s1, s0, -16384
	s_lshl_b32 s1, s1, 11
	s_add_u32 s12, s30, 0x30d2000
	s_addc_u32 s13, s31, 0
	s_add_u32 s12, s12, s1
	s_addc_u32 s13, s13, 0
	global_load_dwordx2 v[132:133], v3, s[12:13]
	global_load_dwordx2 v[134:135], v3, s[12:13] offset:512
	global_load_dwordx2 v[136:137], v3, s[12:13] offset:1024
	global_load_dwordx2 v[138:139], v3, s[12:13] offset:1536
	s_add_i32 s1, s0, -12288
	s_lshl_b32 s1, s1, 11
	s_add_u32 s12, s30, 0x30d2000
	s_addc_u32 s13, s31, 0
	s_add_u32 s12, s12, s1
	s_addc_u32 s13, s13, 0
	global_load_dwordx2 v[140:141], v3, s[12:13]
	global_load_dwordx2 v[142:143], v3, s[12:13] offset:512
	global_load_dwordx2 v[144:145], v3, s[12:13] offset:1024
	global_load_dwordx2 v[146:147], v3, s[12:13] offset:1536
	s_add_i32 s1, s0, -8192
	s_lshl_b32 s1, s1, 11
	s_add_u32 s12, s30, 0x30d2000
	s_addc_u32 s13, s31, 0
	s_add_u32 s12, s12, s1
	s_addc_u32 s13, s13, 0
	global_load_dwordx2 v[148:149], v3, s[12:13]
	global_load_dwordx2 v[150:151], v3, s[12:13] offset:512
	global_load_dwordx2 v[152:153], v3, s[12:13] offset:1024
	global_load_dwordx2 v[154:155], v3, s[12:13] offset:1536
	s_sub_u32 s1, s3, 0x1000
	s_lshr_b32 s1, s1, 12
	s_add_u32 s1, s1, 1
	s_cmp_lt_u32 s3, 0x1000
	s_cselect_b32 s1, 0, s1
	s_mul_i32 s1, s1, 0x6000
	s_add_u32 s14, s30, 0x843000
	s_addc_u32 s15, s31, 0
	s_add_u32 s14, s14, s1
	s_addc_u32 s15, s15, 0
	s_add_u32 s16, s14, 0x1000
	s_addc_u32 s17, s15, 0
	global_load_dwordx4 v[84:87], v2, s[14:15]
	global_load_dwordx4 v[88:91], v2, s[14:15] offset:1024
	global_load_dwordx4 v[92:95], v2, s[14:15] offset:2048
	global_load_dwordx4 v[96:99], v2, s[14:15] offset:3072
	global_load_dwordx4 v[68:71], v2, s[16:17]
	global_load_dwordx4 v[72:75], v2, s[16:17] offset:1024
	global_load_dwordx4 v[76:79], v2, s[16:17] offset:2048
	global_load_dwordx4 v[80:83], v2, s[16:17] offset:3072
	s_add_u32 s18, s30, 0x85e000
	s_addc_u32 s19, s31, 0
	s_bfe_u32 s1, s3, 0x60006
	s_lshl_b32 s1, s1, 11
	s_add_u32 s20, s18, s1
	s_addc_u32 s21, s19, 0
	global_load_dwordx4 v[100:103], v2, s[20:21]
	global_load_dwordx4 v[104:107], v2, s[20:21] offset:1024
	s_and_b32 s1, s3, 63
	s_lshl_b32 s1, s1, 11
	s_add_u32 s20, s18, s1
	s_addc_u32 s21, s19, 0
	global_load_dwordx4 v[108:111], v2, s[20:21]
	global_load_dwordx4 v[112:115], v2, s[20:21] offset:1024
.Lnm6b_nopf1:
	s_mov_b32 s0, s22
	s_lshl_b32 s1, s0, 12
	s_add_u32 s10, s28, s1
	s_addc_u32 s11, s29, 0
	v_lshlrev_b32_e32 v228, 16, v156
	v_and_b32_e32 v229, 0xffff0000, v156
	v_lshlrev_b32_e32 v230, 16, v157
	v_and_b32_e32 v231, 0xffff0000, v157
	v_pk_add_f32 v[212:213], v[212:213], v[228:229]
	v_pk_add_f32 v[214:215], v[214:215], v[230:231]
	v_lshlrev_b32_e32 v232, 16, v164
	v_and_b32_e32 v233, 0xffff0000, v164
	v_lshlrev_b32_e32 v234, 16, v165
	v_and_b32_e32 v235, 0xffff0000, v165
	v_pk_add_f32 v[212:213], v[212:213], v[232:233]
	v_pk_add_f32 v[214:215], v[214:215], v[234:235]
	v_lshlrev_b32_e32 v228, 16, v172
	v_and_b32_e32 v229, 0xffff0000, v172
	v_lshlrev_b32_e32 v230, 16, v173
	v_and_b32_e32 v231, 0xffff0000, v173
	v_pk_add_f32 v[212:213], v[212:213], v[228:229]
	v_pk_add_f32 v[214:215], v[214:215], v[230:231]
	v_lshlrev_b32_e32 v232, 16, v180
	v_and_b32_e32 v233, 0xffff0000, v180
	v_lshlrev_b32_e32 v234, 16, v181
	v_and_b32_e32 v235, 0xffff0000, v181
	v_pk_add_f32 v[212:213], v[212:213], v[232:233]
	v_pk_add_f32 v[214:215], v[214:215], v[234:235]
	v_cvt_pk_bf16_f32 v236, v212, v213
	v_cvt_pk_bf16_f32 v237, v214, v215
	global_store_dwordx2 v3, v[236:237], s[10:11]
	v_pk_mul_f32 v[12:13], v[212:213], v[212:213]
	v_pk_fma_f32 v[12:13], v[214:215], v[214:215], v[12:13]
	v_lshlrev_b32_e32 v228, 16, v158
	v_and_b32_e32 v229, 0xffff0000, v158
	v_lshlrev_b32_e32 v230, 16, v159
	v_and_b32_e32 v231, 0xffff0000, v159
	v_pk_add_f32 v[216:217], v[216:217], v[228:229]
	v_pk_add_f32 v[218:219], v[218:219], v[230:231]
	v_lshlrev_b32_e32 v232, 16, v166
	v_and_b32_e32 v233, 0xffff0000, v166
	v_lshlrev_b32_e32 v234, 16, v167
	v_and_b32_e32 v235, 0xffff0000, v167
	v_pk_add_f32 v[216:217], v[216:217], v[232:233]
	v_pk_add_f32 v[218:219], v[218:219], v[234:235]
	v_lshlrev_b32_e32 v228, 16, v174
	v_and_b32_e32 v229, 0xffff0000, v174
	v_lshlrev_b32_e32 v230, 16, v175
	v_and_b32_e32 v231, 0xffff0000, v175
	v_pk_add_f32 v[216:217], v[216:217], v[228:229]
	v_pk_add_f32 v[218:219], v[218:219], v[230:231]
	v_lshlrev_b32_e32 v232, 16, v182
	v_and_b32_e32 v233, 0xffff0000, v182
	v_lshlrev_b32_e32 v234, 16, v183
	v_and_b32_e32 v235, 0xffff0000, v183
	v_pk_add_f32 v[216:217], v[216:217], v[232:233]
	v_pk_add_f32 v[218:219], v[218:219], v[234:235]
	v_cvt_pk_bf16_f32 v238, v216, v217
	v_cvt_pk_bf16_f32 v239, v218, v219
	global_store_dwordx2 v3, v[238:239], s[10:11] offset:512
	v_pk_fma_f32 v[12:13], v[216:217], v[216:217], v[12:13]
	v_pk_fma_f32 v[12:13], v[218:219], v[218:219], v[12:13]
	v_lshlrev_b32_e32 v228, 16, v160
	v_and_b32_e32 v229, 0xffff0000, v160
	v_lshlrev_b32_e32 v230, 16, v161
	v_and_b32_e32 v231, 0xffff0000, v161
	v_pk_add_f32 v[220:221], v[220:221], v[228:229]
	v_pk_add_f32 v[222:223], v[222:223], v[230:231]
	v_lshlrev_b32_e32 v232, 16, v168
	v_and_b32_e32 v233, 0xffff0000, v168
	v_lshlrev_b32_e32 v234, 16, v169
	v_and_b32_e32 v235, 0xffff0000, v169
	v_pk_add_f32 v[220:221], v[220:221], v[232:233]
	v_pk_add_f32 v[222:223], v[222:223], v[234:235]
	v_lshlrev_b32_e32 v228, 16, v176
	v_and_b32_e32 v229, 0xffff0000, v176
	v_lshlrev_b32_e32 v230, 16, v177
	v_and_b32_e32 v231, 0xffff0000, v177
	v_pk_add_f32 v[220:221], v[220:221], v[228:229]
	v_pk_add_f32 v[222:223], v[222:223], v[230:231]
	v_lshlrev_b32_e32 v232, 16, v184
	v_and_b32_e32 v233, 0xffff0000, v184
	v_lshlrev_b32_e32 v234, 16, v185
	v_and_b32_e32 v235, 0xffff0000, v185
	v_pk_add_f32 v[220:221], v[220:221], v[232:233]
	v_pk_add_f32 v[222:223], v[222:223], v[234:235]
	v_cvt_pk_bf16_f32 v236, v220, v221
	v_cvt_pk_bf16_f32 v237, v222, v223
	global_store_dwordx2 v3, v[236:237], s[10:11] offset:1024
	v_pk_fma_f32 v[12:13], v[220:221], v[220:221], v[12:13]
	v_pk_fma_f32 v[12:13], v[222:223], v[222:223], v[12:13]
	v_lshlrev_b32_e32 v228, 16, v162
	v_and_b32_e32 v229, 0xffff0000, v162
	v_lshlrev_b32_e32 v230, 16, v163
	v_and_b32_e32 v231, 0xffff0000, v163
	v_pk_add_f32 v[224:225], v[224:225], v[228:229]
	v_pk_add_f32 v[226:227], v[226:227], v[230:231]
	v_lshlrev_b32_e32 v232, 16, v170
	v_and_b32_e32 v233, 0xffff0000, v170
	v_lshlrev_b32_e32 v234, 16, v171
	v_and_b32_e32 v235, 0xffff0000, v171
	v_pk_add_f32 v[224:225], v[224:225], v[232:233]
	v_pk_add_f32 v[226:227], v[226:227], v[234:235]
	v_lshlrev_b32_e32 v228, 16, v178
	v_and_b32_e32 v229, 0xffff0000, v178
	v_lshlrev_b32_e32 v230, 16, v179
	v_and_b32_e32 v231, 0xffff0000, v179
	v_pk_add_f32 v[224:225], v[224:225], v[228:229]
	v_pk_add_f32 v[226:227], v[226:227], v[230:231]
	v_lshlrev_b32_e32 v232, 16, v186
	v_and_b32_e32 v233, 0xffff0000, v186
	v_lshlrev_b32_e32 v234, 16, v187
	v_and_b32_e32 v235, 0xffff0000, v187
	v_pk_add_f32 v[224:225], v[224:225], v[232:233]
	v_pk_add_f32 v[226:227], v[226:227], v[234:235]
	v_cvt_pk_bf16_f32 v238, v224, v225
	v_cvt_pk_bf16_f32 v239, v226, v227
	global_store_dwordx2 v3, v[238:239], s[10:11] offset:1536
	v_pk_fma_f32 v[12:13], v[224:225], v[224:225], v[12:13]
	v_pk_fma_f32 v[12:13], v[226:227], v[226:227], v[12:13]
	v_add_f32_e32 v12, v12, v13
	ds_bpermute_b32 v240, v5, v12
	s_waitcnt lgkmcnt(0)
	v_add_f32_e32 v12, v12, v240
	ds_bpermute_b32 v240, v6, v12
	s_waitcnt lgkmcnt(0)
	v_add_f32_e32 v12, v12, v240
	ds_bpermute_b32 v240, v7, v12
	s_waitcnt lgkmcnt(0)
	v_add_f32_e32 v12, v12, v240
	ds_bpermute_b32 v240, v8, v12
	s_waitcnt lgkmcnt(0)
	v_add_f32_e32 v12, v12, v240
	ds_bpermute_b32 v240, v9, v12
	s_waitcnt lgkmcnt(0)
	v_add_f32_e32 v12, v12, v240
	ds_bpermute_b32 v240, v10, v12
	s_waitcnt lgkmcnt(0)
	v_add_f32_e32 v12, v12, v240
	v_fmamk_f32 v16, v12, 0x3a800000, v4
	v_rsq_f32_e32 v16, v16
	s_nop 0
	s_mov_b32 s0, s22
	s_lshl_b32 s1, s0, 11
	s_add_u32 s12, s30, 0x8d2000
	s_addc_u32 s13, s31, 0
	s_add_u32 s12, s12, s1
	s_addc_u32 s13, s13, 0
	v_pk_mul_f32 v[228:229], v[212:213], v[16:17] op_sel_hi:[1,0]
	v_pk_mul_f32 v[230:231], v[214:215], v[16:17] op_sel_hi:[1,0]
	v_pk_fma_f32 v[228:229], v[36:37], v[228:229], v[52:53]
	v_pk_fma_f32 v[230:231], v[38:39], v[230:231], v[54:55]
	v_cvt_pk_bf16_f32 v236, v228, v229
	v_cvt_pk_bf16_f32 v237, v230, v231
	global_store_dwordx2 v3, v[236:237], s[12:13]
	v_pk_mul_f32 v[232:233], v[216:217], v[16:17] op_sel_hi:[1,0]
	v_pk_mul_f32 v[234:235], v[218:219], v[16:17] op_sel_hi:[1,0]
	v_pk_fma_f32 v[232:233], v[40:41], v[232:233], v[56:57]
	v_pk_fma_f32 v[234:235], v[42:43], v[234:235], v[58:59]
	v_cvt_pk_bf16_f32 v238, v232, v233
	v_cvt_pk_bf16_f32 v239, v234, v235
	global_store_dwordx2 v3, v[238:239], s[12:13] offset:512
	v_pk_mul_f32 v[228:229], v[220:221], v[16:17] op_sel_hi:[1,0]
	v_pk_mul_f32 v[230:231], v[222:223], v[16:17] op_sel_hi:[1,0]
	v_pk_fma_f32 v[228:229], v[44:45], v[228:229], v[60:61]
	v_pk_fma_f32 v[230:231], v[46:47], v[230:231], v[62:63]
	v_cvt_pk_bf16_f32 v236, v228, v229
	v_cvt_pk_bf16_f32 v237, v230, v231
	global_store_dwordx2 v3, v[236:237], s[12:13] offset:1024
	v_pk_mul_f32 v[232:233], v[224:225], v[16:17] op_sel_hi:[1,0]
	v_pk_mul_f32 v[234:235], v[226:227], v[16:17] op_sel_hi:[1,0]
	v_pk_fma_f32 v[232:233], v[48:49], v[232:233], v[64:65]
	v_pk_fma_f32 v[234:235], v[50:51], v[234:235], v[66:67]
	v_cvt_pk_bf16_f32 v238, v232, v233
	v_cvt_pk_bf16_f32 v239, v234, v235
	global_store_dwordx2 v3, v[238:239], s[12:13] offset:1536
	s_mov_b32 s22, s3
	s_cmp_lt_u32 s22, 0x5000
	s_cbranch_scc1 .Lnm6b_top0
.Lnm6b_exit:
.LBB0_1121:
	s_or_b64 exec, exec, s[4:5]
	s_getreg_b32 s3, hwreg(HW_REG_XCC_ID, 0, 4)
	s_waitcnt vmcnt(0)
	s_barrier
	s_mov_b64 s[0:1], exec
	v_readlane_b32 s4, v254, 1
	v_readlane_b32 s5, v254, 2
	s_and_b64 s[4:5], s[0:1], s[4:5]
	s_mov_b64 exec, s[4:5]
	s_cbranch_execz .LBB0_1173
	s_add_i32 s4, 0, 0x25000
	s_waitcnt vmcnt(19)
	v_mov_b32_e32 v0, s4
	s_waitcnt vmcnt(0) expcnt(0) lgkmcnt(0)
	ds_read_b32 v2, v0
	s_add_i32 s4, 0, 0x25004
	v_mov_b32_e32 v0, s4
	ds_read_b32 v0, v0
	s_and_b32 s3, s3, 15
	s_waitcnt lgkmcnt(1)
	v_cmp_ne_u32_e32 vcc, 0, v2
	s_cbranch_vccnz .LBB0_1137
	v_readlane_b32 s4, v254, 0
	s_mul_i32 s58, s87, s4
	s_add_u32 s4, s30, 0x8ce200
	s_addc_u32 s5, s31, 0
	s_add_u32 s10, s30, 0x8ce400
	s_addc_u32 s11, s31, 0
	s_add_u32 s12, s30, 0x8ce500
	s_addc_u32 s13, s31, 0
	s_add_u32 s14, s30, 0x8ce600
	s_addc_u32 s15, s31, 0
	s_add_u32 s16, s30, 0x8ce700
	s_addc_u32 s17, s31, 0
	s_add_u32 s18, s30, 0x8ce800
	s_addc_u32 s19, s31, 0
	s_add_u32 s20, s30, 0x8ce900
	s_addc_u32 s21, s31, 0
	s_add_u32 s22, s30, 0x8cea00
	s_addc_u32 s23, s31, 0
	s_add_u32 s24, s30, 0x8ceb00
	s_addc_u32 s25, s31, 0
	s_add_u32 s26, s30, 0x8cec00
	s_addc_u32 s27, s31, 0
	s_add_u32 s36, s30, 0x8ced00
	s_addc_u32 s37, s31, 0
	s_add_u32 s38, s30, 0x8cee00
	s_addc_u32 s39, s31, 0
	s_add_u32 s40, s30, 0x8cef00
	s_addc_u32 s41, s31, 0
	s_add_u32 s42, s30, 0x8cf000
	s_addc_u32 s43, s31, 0
	s_add_u32 s44, s30, 0x8cf100
	s_addc_u32 s45, s31, 0
	s_add_u32 s46, s30, 0x8cf200
	s_addc_u32 s47, s31, 0
	s_add_u32 s48, s30, 0x8cf300
	s_mul_i32 s58, s58, s86
	s_addc_u32 s49, s31, 0
	s_mov_b32 s59, 1
	v_mov_b32_e32 v16, 0
	s_branch .LBB0_1125

	.amdhsa_kernel _Z14fwd_megakernel6Params
		.amdhsa_group_segment_fixed_size 0
		.amdhsa_private_segment_fixed_size 0
		.amdhsa_kernarg_size 464
		.amdhsa_user_sgpr_count 2
		.amdhsa_user_sgpr_dispatch_ptr 0
		.amdhsa_user_sgpr_queue_ptr 0
		.amdhsa_user_sgpr_kernarg_segment_ptr 1
		.amdhsa_user_sgpr_dispatch_id 0
		.amdhsa_user_sgpr_kernarg_preload_length 0
		.amdhsa_user_sgpr_kernarg_preload_offset 0
		.amdhsa_user_sgpr_private_segment_size 0
		.amdhsa_uses_dynamic_stack 0
		.amdhsa_enable_private_segment 0
		.amdhsa_system_sgpr_workgroup_id_x 1
		.amdhsa_system_sgpr_workgroup_id_y 0
		.amdhsa_system_sgpr_workgroup_id_z 0
		.amdhsa_system_sgpr_workgroup_info 0
		.amdhsa_system_vgpr_workitem_id 2
		.amdhsa_next_free_vgpr 255
		.amdhsa_next_free_sgpr 102
		.amdhsa_accum_offset 256
		.amdhsa_reserve_vcc 1
		.amdhsa_float_round_mode_32 0
		.amdhsa_float_round_mode_16_64 0
		.amdhsa_float_denorm_mode_32 3
		.amdhsa_float_denorm_mode_16_64 3
		.amdhsa_dx10_clamp 1
		.amdhsa_ieee_mode 1
		.amdhsa_fp16_overflow 0
		.amdhsa_tg_split 0
		.amdhsa_exception_fp_ieee_invalid_op 0
		.amdhsa_exception_fp_denorm_src 0
		.amdhsa_exception_fp_ieee_div_zero 0
		.amdhsa_exception_fp_ieee_overflow 0
		.amdhsa_exception_fp_ieee_underflow 0
		.amdhsa_exception_fp_ieee_inexact 0
		.amdhsa_exception_int_div_zero 0
	.end_amdhsa_kernel

amdhsa.kernels:
  - .agpr_count:     0
    .args:
      - .offset:         0
        .size:           208
        .value_kind:     by_value
      - .offset:         208
        .size:           4
        .value_kind:     hidden_block_count_x
      - .offset:         212
        .size:           4
        .value_kind:     hidden_block_count_y
      - .offset:         216
        .size:           4
        .value_kind:     hidden_block_count_z
      - .offset:         220
        .size:           2
        .value_kind:     hidden_group_size_x
      - .offset:         222
        .size:           2
        .value_kind:     hidden_group_size_y
      - .offset:         224
        .size:           2
        .value_kind:     hidden_group_size_z
      - .offset:         226
        .size:           2
        .value_kind:     hidden_remainder_x
      - .offset:         228
        .size:           2
        .value_kind:     hidden_remainder_y
      - .offset:         230
        .size:           2
        .value_kind:     hidden_remainder_z
      - .offset:         248
        .size:           8
        .value_kind:     hidden_global_offset_x
      - .offset:         256
        .size:           8
        .value_kind:     hidden_global_offset_y
      - .offset:         264
        .size:           8
        .value_kind:     hidden_global_offset_z
      - .offset:         272
        .size:           2
        .value_kind:     hidden_grid_dims
      - .offset:         296
        .size:           8
        .value_kind:     hidden_multigrid_sync_arg
      - .offset:         328
        .size:           4
        .value_kind:     hidden_dynamic_lds_size
    .group_segment_fixed_size: 0
    .kernarg_segment_align: 8
    .kernarg_segment_size: 464
    .language:       OpenCL C
    .language_version:
      - 2
      - 0
    .max_flat_workgroup_size: 512
    .name:           _Z14fwd_megakernel6Params
    .private_segment_fixed_size: 0
    .sgpr_count:     108
    .sgpr_spill_count: 47
    .symbol:         _Z14fwd_megakernel6Params.kd
    .uniform_work_group_size: 1
    .uses_dynamic_stack: false
    .vgpr_count:     255
    .vgpr_spill_count: 0
    .wavefront_size: 64
